# weight conversion transposing bodies: eight LDS read-backs issued together with one wait (was 8 serial read+wait+pack)
# speedup vs baseline: 1.0053x; 1.0036x over previous
.LBB0_83:
	s_or_b64 exec, exec, s[2:3]
	s_waitcnt lgkmcnt(0)
	s_barrier
	s_and_saveexec_b64 s[2:3], s[6:7]
	s_cbranch_execz .LBB0_56
	v_add_u32_e32 v0, v10, v18
	v_cmp_gt_i32_e32 vcc, s70, v0
	s_and_b64 exec, exec, vcc
	s_cbranch_execz .LBB0_56
	ds_read2_b32 v[64:65], v26 offset1:65
	v_add_u32_e32 v1, 0x400, v26
	v_ashrrev_i32_e32 v9, 31, v8
	ds_read2_b32 v[66:67], v26 offset0:130 offset1:195
	ds_read2_b32 v[68:69], v1 offset0:4 offset1:69
	ds_read2_b32 v[70:71], v1 offset0:134 offset1:199
	v_add_u32_e32 v1, 0x800, v26
	ds_read2_b32 v[72:73], v1 offset0:8 offset1:73
	ds_read2_b32 v[74:75], v1 offset0:138 offset1:203
	v_add_u32_e32 v1, 0xc00, v26
	ds_read2_b32 v[76:77], v1 offset0:12 offset1:77
	ds_read2_b32 v[78:79], v1 offset0:142 offset1:207
	v_ashrrev_i32_e32 v1, 31, v0
	v_lshlrev_b64 v[0:1], 11, v[0:1]
	v_lshl_add_u64 v[0:1], s[18:19], 0, v[0:1]
	v_lshl_add_u64 v[0:1], v[8:9], 1, v[0:1]
	v_lshl_add_u64 v[0:1], v[0:1], 0, v[168:169]
	s_waitcnt lgkmcnt(0)
	v_cvt_pk_bf16_f32 v10, v64, v65
	v_cvt_pk_bf16_f32 v11, v66, v67
	v_cvt_pk_bf16_f32 v12, v68, v69
	v_cvt_pk_bf16_f32 v13, v70, v71
	v_cvt_pk_bf16_f32 v28, v72, v73
	v_cvt_pk_bf16_f32 v29, v74, v75
	v_cvt_pk_bf16_f32 v30, v76, v77
	v_cvt_pk_bf16_f32 v31, v78, v79
	global_store_dwordx4 v[0:1], v[10:13], off
	global_store_dwordx4 v[0:1], v[28:31], off offset:16
	s_branch .LBB0_56

.LBB0_115:
	s_or_b64 exec, exec, s[12:13]
	s_waitcnt lgkmcnt(0)
	s_barrier
	s_and_saveexec_b64 s[8:9], s[6:7]
	s_cbranch_execz .LBB0_88
	v_add_u32_e32 v0, v10, v18
	v_cmp_gt_i32_e32 vcc, s69, v0
	s_and_b64 exec, exec, vcc
	s_cbranch_execz .LBB0_88
	ds_read2_b32 v[64:65], v26 offset1:65
	v_add_u32_e32 v1, 0x400, v26
	v_ashrrev_i32_e32 v9, 31, v8
	ds_read2_b32 v[66:67], v26 offset0:130 offset1:195
	ds_read2_b32 v[68:69], v1 offset0:4 offset1:69
	ds_read2_b32 v[70:71], v1 offset0:134 offset1:199
	v_add_u32_e32 v1, 0x800, v26
	ds_read2_b32 v[72:73], v1 offset0:8 offset1:73
	ds_read2_b32 v[74:75], v1 offset0:138 offset1:203
	v_add_u32_e32 v1, 0xc00, v26
	ds_read2_b32 v[76:77], v1 offset0:12 offset1:77
	ds_read2_b32 v[78:79], v1 offset0:142 offset1:207
	v_ashrrev_i32_e32 v1, 31, v0
	v_lshlrev_b64 v[0:1], 11, v[0:1]
	v_lshl_add_u64 v[0:1], s[2:3], 0, v[0:1]
	v_lshl_add_u64 v[0:1], v[8:9], 1, v[0:1]
	v_lshl_add_u64 v[0:1], v[0:1], 0, v[168:169]
	s_waitcnt lgkmcnt(0)
	v_cvt_pk_bf16_f32 v10, v64, v65
	v_cvt_pk_bf16_f32 v11, v66, v67
	v_cvt_pk_bf16_f32 v12, v68, v69
	v_cvt_pk_bf16_f32 v13, v70, v71
	v_cvt_pk_bf16_f32 v28, v72, v73
	v_cvt_pk_bf16_f32 v29, v74, v75
	v_cvt_pk_bf16_f32 v30, v76, v77
	v_cvt_pk_bf16_f32 v31, v78, v79
	global_store_dwordx4 v[0:1], v[10:13], off
	global_store_dwordx4 v[0:1], v[28:31], off offset:16
	s_branch .LBB0_88

.LBB0_143:
	s_or_b64 exec, exec, s[34:35]
	s_xor_b64 s[34:35], s[12:13], -1
	s_waitcnt lgkmcnt(0)
	s_barrier
	s_and_saveexec_b64 s[12:13], s[34:35]
	s_cbranch_execz .LBB0_120
	ds_read2_b32 v[64:65], v20 offset1:65
	ds_read2_b32 v[66:67], v20 offset0:130 offset1:195
	v_add_u32_e32 v11, 0x400, v20
	ds_read2_b32 v[68:69], v11 offset0:134 offset1:199
	v_cndmask_b32_e64 v14, v10, 0, s[10:11]
	ds_read2_b32 v[70:71], v11 offset0:4 offset1:69
	v_add_u32_e32 v11, 0x800, v20
	ds_read2_b32 v[72:73], v11 offset0:138 offset1:203
	v_ashrrev_i32_e32 v15, 31, v14
	v_lshl_add_u64 v[14:15], v[14:15], 1, v[8:9]
	ds_read2_b32 v[74:75], v11 offset0:8 offset1:73
	v_add_u32_e32 v11, 0xc00, v20
	ds_read2_b32 v[76:77], v11 offset0:142 offset1:207
	ds_read2_b32 v[78:79], v11 offset0:12 offset1:77
	s_waitcnt lgkmcnt(0)
	v_cvt_pk_bf16_f32 v0, v64, v65
	v_cvt_pk_bf16_f32 v1, v66, v67
	v_cvt_pk_bf16_f32 v2, v70, v71
	v_cvt_pk_bf16_f32 v3, v68, v69
	v_cvt_pk_bf16_f32 v22, v74, v75
	v_cvt_pk_bf16_f32 v23, v72, v73
	v_cvt_pk_bf16_f32 v24, v78, v79
	v_cvt_pk_bf16_f32 v25, v76, v77
	global_store_dwordx4 v[14:15], v[0:3], off
	global_store_dwordx4 v[14:15], v[22:25], off offset:16
	s_branch .LBB0_120

.LBB0_171:
	s_or_b64 exec, exec, s[2:3]
	s_xor_b64 s[12:13], s[12:13], -1
	s_waitcnt lgkmcnt(0)
	s_barrier
	s_and_saveexec_b64 s[2:3], s[12:13]
	s_cbranch_execz .LBB0_148
	ds_read2_b32 v[64:65], v20 offset1:65
	ds_read2_b32 v[66:67], v20 offset0:130 offset1:195
	v_add_u32_e32 v11, 0x400, v20
	ds_read2_b32 v[68:69], v11 offset0:134 offset1:199
	v_cndmask_b32_e64 v14, v10, 0, s[10:11]
	ds_read2_b32 v[70:71], v11 offset0:4 offset1:69
	v_add_u32_e32 v11, 0x800, v20
	ds_read2_b32 v[72:73], v11 offset0:138 offset1:203
	v_ashrrev_i32_e32 v15, 31, v14
	v_lshl_add_u64 v[14:15], v[14:15], 1, v[8:9]
	ds_read2_b32 v[74:75], v11 offset0:8 offset1:73
	v_add_u32_e32 v11, 0xc00, v20
	ds_read2_b32 v[76:77], v11 offset0:142 offset1:207
	ds_read2_b32 v[78:79], v11 offset0:12 offset1:77
	s_waitcnt lgkmcnt(0)
	v_cvt_pk_bf16_f32 v0, v64, v65
	v_cvt_pk_bf16_f32 v1, v66, v67
	v_cvt_pk_bf16_f32 v2, v70, v71
	v_cvt_pk_bf16_f32 v3, v68, v69
	v_cvt_pk_bf16_f32 v22, v74, v75
	v_cvt_pk_bf16_f32 v23, v72, v73
	v_cvt_pk_bf16_f32 v24, v78, v79
	v_cvt_pk_bf16_f32 v25, v76, v77
	global_store_dwordx4 v[14:15], v[0:3], off
	global_store_dwordx4 v[14:15], v[22:25], off offset:16
	s_branch .LBB0_148

.LBB0_202:
	s_or_b64 exec, exec, s[34:35]
	s_waitcnt lgkmcnt(0)
	s_barrier
	s_and_saveexec_b64 s[10:11], s[8:9]
	s_cbranch_execz .LBB0_175
	v_add_u32_e32 v0, v10, v18
	v_cmp_gt_i32_e32 vcc, s70, v0
	s_and_b64 exec, exec, vcc
	s_cbranch_execz .LBB0_175
	ds_read2_b32 v[64:65], v26 offset1:65
	v_add_u32_e32 v1, 0x400, v26
	v_ashrrev_i32_e32 v9, 31, v8
	ds_read2_b32 v[66:67], v26 offset0:130 offset1:195
	ds_read2_b32 v[68:69], v1 offset0:4 offset1:69
	ds_read2_b32 v[70:71], v1 offset0:134 offset1:199
	v_add_u32_e32 v1, 0x800, v26
	ds_read2_b32 v[72:73], v1 offset0:8 offset1:73
	ds_read2_b32 v[74:75], v1 offset0:138 offset1:203
	v_add_u32_e32 v1, 0xc00, v26
	ds_read2_b32 v[76:77], v1 offset0:12 offset1:77
	ds_read2_b32 v[78:79], v1 offset0:142 offset1:207
	v_ashrrev_i32_e32 v1, 31, v0
	v_lshlrev_b64 v[0:1], 11, v[0:1]
	v_lshl_add_u64 v[0:1], s[2:3], 0, v[0:1]
	v_lshl_add_u64 v[0:1], v[8:9], 1, v[0:1]
	v_lshl_add_u64 v[0:1], v[0:1], 0, v[168:169]
	s_waitcnt lgkmcnt(0)
	v_cvt_pk_bf16_f32 v10, v64, v65
	v_cvt_pk_bf16_f32 v11, v66, v67
	v_cvt_pk_bf16_f32 v12, v68, v69
	v_cvt_pk_bf16_f32 v13, v70, v71
	v_cvt_pk_bf16_f32 v28, v72, v73
	v_cvt_pk_bf16_f32 v29, v74, v75
	v_cvt_pk_bf16_f32 v30, v76, v77
	v_cvt_pk_bf16_f32 v31, v78, v79
	global_store_dwordx4 v[0:1], v[10:13], off
	global_store_dwordx4 v[0:1], v[28:31], off offset:16
	s_branch .LBB0_175

.LBB0_266:
	s_or_b64 exec, exec, s[34:35]
	s_waitcnt lgkmcnt(0)
	s_barrier
	s_and_saveexec_b64 s[12:13], s[10:11]
	s_cbranch_execz .LBB0_239
	v_add_u32_e32 v0, v10, v18
	v_cmp_gt_i32_e32 vcc, s69, v0
	s_and_b64 exec, exec, vcc
	s_cbranch_execz .LBB0_239
	ds_read2_b32 v[64:65], v26 offset1:65
	v_add_u32_e32 v1, 0x400, v26
	v_ashrrev_i32_e32 v9, 31, v8
	ds_read2_b32 v[66:67], v26 offset0:130 offset1:195
	ds_read2_b32 v[68:69], v1 offset0:4 offset1:69
	ds_read2_b32 v[70:71], v1 offset0:134 offset1:199
	v_add_u32_e32 v1, 0x800, v26
	ds_read2_b32 v[72:73], v1 offset0:8 offset1:73
	ds_read2_b32 v[74:75], v1 offset0:138 offset1:203
	v_add_u32_e32 v1, 0xc00, v26
	ds_read2_b32 v[76:77], v1 offset0:12 offset1:77
	ds_read2_b32 v[78:79], v1 offset0:142 offset1:207
	v_ashrrev_i32_e32 v1, 31, v0
	v_lshlrev_b64 v[0:1], 11, v[0:1]
	v_lshl_add_u64 v[0:1], s[2:3], 0, v[0:1]
	v_lshl_add_u64 v[0:1], v[8:9], 1, v[0:1]
	v_lshl_add_u64 v[0:1], v[0:1], 0, v[168:169]
	s_waitcnt lgkmcnt(0)
	v_cvt_pk_bf16_f32 v10, v64, v65
	v_cvt_pk_bf16_f32 v11, v66, v67
	v_cvt_pk_bf16_f32 v12, v68, v69
	v_cvt_pk_bf16_f32 v13, v70, v71
	v_cvt_pk_bf16_f32 v28, v72, v73
	v_cvt_pk_bf16_f32 v29, v74, v75
	v_cvt_pk_bf16_f32 v30, v76, v77
	v_cvt_pk_bf16_f32 v31, v78, v79
	global_store_dwordx4 v[0:1], v[10:13], off
	global_store_dwordx4 v[0:1], v[28:31], off offset:16
	s_branch .LBB0_239

.LBB0_330:
	s_or_b64 exec, exec, s[34:35]
	s_waitcnt lgkmcnt(0)
	s_barrier
	s_and_saveexec_b64 s[12:13], s[10:11]
	s_cbranch_execz .LBB0_303
	v_add_u32_e32 v0, v10, v18
	v_cmp_gt_i32_e32 vcc, s70, v0
	s_and_b64 exec, exec, vcc
	s_cbranch_execz .LBB0_303
	ds_read2_b32 v[64:65], v26 offset1:65
	v_add_u32_e32 v1, 0x400, v26
	v_ashrrev_i32_e32 v9, 31, v8
	ds_read2_b32 v[66:67], v26 offset0:130 offset1:195
	ds_read2_b32 v[68:69], v1 offset0:4 offset1:69
	ds_read2_b32 v[70:71], v1 offset0:134 offset1:199
	v_add_u32_e32 v1, 0x800, v26
	ds_read2_b32 v[72:73], v1 offset0:8 offset1:73
	ds_read2_b32 v[74:75], v1 offset0:138 offset1:203
	v_add_u32_e32 v1, 0xc00, v26
	ds_read2_b32 v[76:77], v1 offset0:12 offset1:77
	ds_read2_b32 v[78:79], v1 offset0:142 offset1:207
	v_ashrrev_i32_e32 v1, 31, v0
	v_lshlrev_b64 v[0:1], 11, v[0:1]
	v_lshl_add_u64 v[0:1], s[2:3], 0, v[0:1]
	v_lshl_add_u64 v[0:1], v[8:9], 1, v[0:1]
	v_lshl_add_u64 v[0:1], v[0:1], 0, v[168:169]
	s_waitcnt lgkmcnt(0)
	v_cvt_pk_bf16_f32 v10, v64, v65
	v_cvt_pk_bf16_f32 v11, v66, v67
	v_cvt_pk_bf16_f32 v12, v68, v69
	v_cvt_pk_bf16_f32 v13, v70, v71
	v_cvt_pk_bf16_f32 v28, v72, v73
	v_cvt_pk_bf16_f32 v29, v74, v75
	v_cvt_pk_bf16_f32 v30, v76, v77
	v_cvt_pk_bf16_f32 v31, v78, v79
	global_store_dwordx4 v[0:1], v[10:13], off
	global_store_dwordx4 v[0:1], v[28:31], off offset:16
	s_branch .LBB0_303

.LBB0_397:
	s_or_b64 exec, exec, s[36:37]
	s_waitcnt lgkmcnt(0)
	s_barrier
	s_and_saveexec_b64 s[12:13], s[10:11]
	s_cbranch_execz .LBB0_370
	v_add_u32_e32 v0, v10, v18
	v_cmp_gt_i32_e32 vcc, s76, v0
	s_and_b64 exec, exec, vcc
	s_cbranch_execz .LBB0_370
	ds_read2_b32 v[64:65], v26 offset1:65
	v_add_u32_e32 v1, 0x400, v26
	v_ashrrev_i32_e32 v9, 31, v8
	ds_read2_b32 v[66:67], v26 offset0:130 offset1:195
	ds_read2_b32 v[68:69], v1 offset0:4 offset1:69
	ds_read2_b32 v[70:71], v1 offset0:134 offset1:199
	v_add_u32_e32 v1, 0x800, v26
	ds_read2_b32 v[72:73], v1 offset0:8 offset1:73
	ds_read2_b32 v[74:75], v1 offset0:138 offset1:203
	v_add_u32_e32 v1, 0xc00, v26
	ds_read2_b32 v[76:77], v1 offset0:12 offset1:77
	ds_read2_b32 v[78:79], v1 offset0:142 offset1:207
	v_ashrrev_i32_e32 v1, 31, v0
	v_lshlrev_b64 v[0:1], 9, v[0:1]
	v_lshl_add_u64 v[0:1], s[2:3], 0, v[0:1]
	v_lshl_add_u64 v[0:1], v[8:9], 1, v[0:1]
	v_lshl_add_u64 v[0:1], v[0:1], 0, v[168:169]
	s_waitcnt lgkmcnt(0)
	v_cvt_pk_bf16_f32 v10, v64, v65
	v_cvt_pk_bf16_f32 v11, v66, v67
	v_cvt_pk_bf16_f32 v12, v68, v69
	v_cvt_pk_bf16_f32 v13, v70, v71
	v_cvt_pk_bf16_f32 v28, v72, v73
	v_cvt_pk_bf16_f32 v29, v74, v75
	v_cvt_pk_bf16_f32 v30, v76, v77
	v_cvt_pk_bf16_f32 v31, v78, v79
	global_store_dwordx4 v[0:1], v[10:13], off
	global_store_dwordx4 v[0:1], v[28:31], off offset:16
	s_branch .LBB0_370

.LBB0_429:
	s_or_b64 exec, exec, s[34:35]
	s_waitcnt lgkmcnt(0)
	s_barrier
	s_and_saveexec_b64 s[10:11], s[8:9]
	s_cbranch_execz .LBB0_402
	v_add_u32_e32 v0, v10, v18
	v_cmp_gt_i32_e32 vcc, s92, v0
	s_and_b64 exec, exec, vcc
	s_cbranch_execz .LBB0_402
	ds_read2_b32 v[64:65], v26 offset1:65
	v_add_u32_e32 v1, 0x400, v26
	v_ashrrev_i32_e32 v9, 31, v8
	ds_read2_b32 v[66:67], v26 offset0:130 offset1:195
	ds_read2_b32 v[68:69], v1 offset0:4 offset1:69
	ds_read2_b32 v[70:71], v1 offset0:134 offset1:199
	v_add_u32_e32 v1, 0x800, v26
	ds_read2_b32 v[72:73], v1 offset0:8 offset1:73
	ds_read2_b32 v[74:75], v1 offset0:138 offset1:203
	v_add_u32_e32 v1, 0xc00, v26
	ds_read2_b32 v[76:77], v1 offset0:12 offset1:77
	ds_read2_b32 v[78:79], v1 offset0:142 offset1:207
	v_ashrrev_i32_e32 v1, 31, v0
	v_lshlrev_b64 v[0:1], 8, v[0:1]
	v_lshl_add_u64 v[0:1], s[2:3], 0, v[0:1]
	v_lshl_add_u64 v[0:1], v[8:9], 1, v[0:1]
	v_lshl_add_u64 v[0:1], v[0:1], 0, v[168:169]
	s_waitcnt lgkmcnt(0)
	v_cvt_pk_bf16_f32 v10, v64, v65
	v_cvt_pk_bf16_f32 v11, v66, v67
	v_cvt_pk_bf16_f32 v12, v68, v69
	v_cvt_pk_bf16_f32 v13, v70, v71
	v_cvt_pk_bf16_f32 v28, v72, v73
	v_cvt_pk_bf16_f32 v29, v74, v75
	v_cvt_pk_bf16_f32 v30, v76, v77
	v_cvt_pk_bf16_f32 v31, v78, v79
	global_store_dwordx4 v[0:1], v[10:13], off
	global_store_dwordx4 v[0:1], v[28:31], off offset:16
	s_branch .LBB0_402

.LBB0_461:
	s_or_b64 exec, exec, s[38:39]
	s_waitcnt lgkmcnt(0)
	s_barrier
	s_and_saveexec_b64 s[10:11], s[8:9]
	s_cbranch_execz .LBB0_434
	v_add_u32_e32 v0, v10, v18
	v_cmp_gt_i32_e32 vcc, s92, v0
	s_and_b64 exec, exec, vcc
	s_cbranch_execz .LBB0_434
	ds_read2_b32 v[64:65], v26 offset1:65
	v_add_u32_e32 v1, 0x400, v26
	v_ashrrev_i32_e32 v9, 31, v8
	ds_read2_b32 v[66:67], v26 offset0:130 offset1:195
	ds_read2_b32 v[68:69], v1 offset0:4 offset1:69
	ds_read2_b32 v[70:71], v1 offset0:134 offset1:199
	v_add_u32_e32 v1, 0x800, v26
	ds_read2_b32 v[72:73], v1 offset0:8 offset1:73
	ds_read2_b32 v[74:75], v1 offset0:138 offset1:203
	v_add_u32_e32 v1, 0xc00, v26
	ds_read2_b32 v[76:77], v1 offset0:12 offset1:77
	ds_read2_b32 v[78:79], v1 offset0:142 offset1:207
	v_ashrrev_i32_e32 v1, 31, v0
	v_lshlrev_b64 v[0:1], 11, v[0:1]
	v_lshl_add_u64 v[0:1], s[30:31], 0, v[0:1]
	v_lshl_add_u64 v[0:1], v[8:9], 1, v[0:1]
	v_lshl_add_u64 v[0:1], v[0:1], 0, v[168:169]
	s_waitcnt lgkmcnt(0)
	v_cvt_pk_bf16_f32 v10, v64, v65
	v_cvt_pk_bf16_f32 v11, v66, v67
	v_cvt_pk_bf16_f32 v12, v68, v69
	v_cvt_pk_bf16_f32 v13, v70, v71
	v_cvt_pk_bf16_f32 v28, v72, v73
	v_cvt_pk_bf16_f32 v29, v74, v75
	v_cvt_pk_bf16_f32 v30, v76, v77
	v_cvt_pk_bf16_f32 v31, v78, v79
	global_store_dwordx4 v[0:1], v[10:13], off
	global_store_dwordx4 v[0:1], v[28:31], off offset:16
	s_branch .LBB0_434

.LBB0_525:
	s_or_b64 exec, exec, s[30:31]
	s_waitcnt lgkmcnt(0)
	s_barrier
	s_and_saveexec_b64 s[8:9], s[6:7]
	s_cbranch_execz .LBB0_498
	v_add_u32_e32 v0, v10, v18
	v_cmp_gt_i32_e32 vcc, s92, v0
	s_and_b64 exec, exec, vcc
	s_cbranch_execz .LBB0_498
	ds_read2_b32 v[64:65], v26 offset1:65
	v_add_u32_e32 v1, 0x400, v26
	v_ashrrev_i32_e32 v9, 31, v8
	ds_read2_b32 v[66:67], v26 offset0:130 offset1:195
	ds_read2_b32 v[68:69], v1 offset0:4 offset1:69
	ds_read2_b32 v[70:71], v1 offset0:134 offset1:199
	v_add_u32_e32 v1, 0x800, v26
	ds_read2_b32 v[72:73], v1 offset0:8 offset1:73
	ds_read2_b32 v[74:75], v1 offset0:138 offset1:203
	v_add_u32_e32 v1, 0xc00, v26
	ds_read2_b32 v[76:77], v1 offset0:12 offset1:77
	ds_read2_b32 v[78:79], v1 offset0:142 offset1:207
	v_ashrrev_i32_e32 v1, 31, v0
	v_lshlrev_b64 v[0:1], 11, v[0:1]
	v_lshl_add_u64 v[0:1], s[12:13], 0, v[0:1]
	v_lshl_add_u64 v[0:1], v[8:9], 1, v[0:1]
	v_lshl_add_u64 v[0:1], v[0:1], 0, v[168:169]
	s_waitcnt lgkmcnt(0)
	v_cvt_pk_bf16_f32 v10, v64, v65
	v_cvt_pk_bf16_f32 v11, v66, v67
	v_cvt_pk_bf16_f32 v12, v68, v69
	v_cvt_pk_bf16_f32 v13, v70, v71
	v_cvt_pk_bf16_f32 v28, v72, v73
	v_cvt_pk_bf16_f32 v29, v74, v75
	v_cvt_pk_bf16_f32 v30, v76, v77
	v_cvt_pk_bf16_f32 v31, v78, v79
	global_store_dwordx4 v[0:1], v[10:13], off
	global_store_dwordx4 v[0:1], v[28:31], off offset:16
	s_branch .LBB0_498

.LBB0_557:
	s_or_b64 exec, exec, s[36:37]
	s_waitcnt lgkmcnt(0)
	s_barrier
	s_and_saveexec_b64 s[8:9], s[6:7]
	s_cbranch_execz .LBB0_530
	v_add_u32_e32 v0, v10, v18
	v_cmp_gt_i32_e32 vcc, s92, v0
	s_and_b64 exec, exec, vcc
	s_cbranch_execz .LBB0_530
	ds_read2_b32 v[64:65], v26 offset1:65
	v_add_u32_e32 v1, 0x400, v26
	v_ashrrev_i32_e32 v9, 31, v8
	ds_read2_b32 v[66:67], v26 offset0:130 offset1:195
	ds_read2_b32 v[68:69], v1 offset0:4 offset1:69
	ds_read2_b32 v[70:71], v1 offset0:134 offset1:199
	v_add_u32_e32 v1, 0x800, v26
	ds_read2_b32 v[72:73], v1 offset0:8 offset1:73
	ds_read2_b32 v[74:75], v1 offset0:138 offset1:203
	v_add_u32_e32 v1, 0xc00, v26
	ds_read2_b32 v[76:77], v1 offset0:12 offset1:77
	ds_read2_b32 v[78:79], v1 offset0:142 offset1:207
	v_ashrrev_i32_e32 v1, 31, v0
	v_lshlrev_b64 v[0:1], 11, v[0:1]
	v_lshl_add_u64 v[0:1], s[30:31], 0, v[0:1]
	v_lshl_add_u64 v[0:1], v[8:9], 1, v[0:1]
	v_lshl_add_u64 v[0:1], v[0:1], 0, v[168:169]
	s_waitcnt lgkmcnt(0)
	v_cvt_pk_bf16_f32 v10, v64, v65
	v_cvt_pk_bf16_f32 v11, v66, v67
	v_cvt_pk_bf16_f32 v12, v68, v69
	v_cvt_pk_bf16_f32 v13, v70, v71
	v_cvt_pk_bf16_f32 v28, v72, v73
	v_cvt_pk_bf16_f32 v29, v74, v75
	v_cvt_pk_bf16_f32 v30, v76, v77
	v_cvt_pk_bf16_f32 v31, v78, v79
	global_store_dwordx4 v[0:1], v[10:13], off
	global_store_dwordx4 v[0:1], v[28:31], off offset:16
	s_branch .LBB0_530

.LBB0_590:
	s_or_b64 exec, exec, s[34:35]
	s_waitcnt lgkmcnt(0)
	s_barrier
	s_and_saveexec_b64 s[10:11], s[8:9]
	s_cbranch_execz .LBB0_563
	v_add_u32_e32 v0, v10, v18
	v_cmp_gt_i32_e32 vcc, s92, v0
	s_and_b64 exec, exec, vcc
	s_cbranch_execz .LBB0_563
	ds_read2_b32 v[64:65], v26 offset1:65
	v_add_u32_e32 v1, 0x400, v26
	v_ashrrev_i32_e32 v9, 31, v8
	ds_read2_b32 v[66:67], v26 offset0:130 offset1:195
	ds_read2_b32 v[68:69], v1 offset0:4 offset1:69
	ds_read2_b32 v[70:71], v1 offset0:134 offset1:199
	v_add_u32_e32 v1, 0x800, v26
	ds_read2_b32 v[72:73], v1 offset0:8 offset1:73
	ds_read2_b32 v[74:75], v1 offset0:138 offset1:203
	v_add_u32_e32 v1, 0xc00, v26
	ds_read2_b32 v[76:77], v1 offset0:12 offset1:77
	ds_read2_b32 v[78:79], v1 offset0:142 offset1:207
	v_ashrrev_i32_e32 v1, 31, v0
	v_lshlrev_b64 v[0:1], 11, v[0:1]
	v_lshl_add_u64 v[0:1], s[22:23], 0, v[0:1]
	v_lshl_add_u64 v[0:1], v[8:9], 1, v[0:1]
	v_lshl_add_u64 v[0:1], v[0:1], 0, v[168:169]
	s_waitcnt lgkmcnt(0)
	v_cvt_pk_bf16_f32 v10, v64, v65
	v_cvt_pk_bf16_f32 v11, v66, v67
	v_cvt_pk_bf16_f32 v12, v68, v69
	v_cvt_pk_bf16_f32 v13, v70, v71
	v_cvt_pk_bf16_f32 v28, v72, v73
	v_cvt_pk_bf16_f32 v29, v74, v75
	v_cvt_pk_bf16_f32 v30, v76, v77
	v_cvt_pk_bf16_f32 v31, v78, v79
	global_store_dwordx4 v[0:1], v[10:13], off
	global_store_dwordx4 v[0:1], v[28:31], off offset:16
	s_branch .LBB0_563

.LBB0_607:
	s_or_b64 exec, exec, s[8:9]
	s_waitcnt lgkmcnt(0)
	s_barrier
	s_and_saveexec_b64 s[6:7], vcc
	s_cbranch_execz .LBB0_596
	v_add_u32_e32 v0, v12, v16
	v_cmp_gt_i32_e32 vcc, s92, v0
	s_and_b64 exec, exec, vcc
	s_cbranch_execz .LBB0_596
	ds_read2_b32 v[64:65], v21 offset1:65
	ds_read2_b32 v[66:67], v21 offset0:130 offset1:195
	v_add_u32_e32 v1, 0x400, v21
	ds_read2_b32 v[68:69], v1 offset0:134 offset1:199
	v_ashrrev_i32_e32 v11, 31, v10
	ds_read2_b32 v[70:71], v1 offset0:4 offset1:69
	v_add_u32_e32 v1, 0x800, v21
	ds_read2_b32 v[72:73], v1 offset0:8 offset1:73
	ds_read2_b32 v[74:75], v1 offset0:138 offset1:203
	v_add_u32_e32 v1, 0xc00, v21
	ds_read2_b32 v[76:77], v1 offset0:12 offset1:77
	ds_read2_b32 v[78:79], v1 offset0:142 offset1:207
	v_ashrrev_i32_e32 v1, 31, v0
	v_lshlrev_b64 v[0:1], 11, v[0:1]
	v_lshl_add_u64 v[0:1], s[2:3], 0, v[0:1]
	v_lshl_add_u64 v[0:1], v[10:11], 1, v[0:1]
	v_lshl_add_u64 v[0:1], v[0:1], 0, v[168:169]
	s_waitcnt lgkmcnt(0)
	v_cvt_pk_bf16_f32 v2, v64, v65
	v_cvt_pk_bf16_f32 v3, v66, v67
	v_cvt_pk_bf16_f32 v4, v70, v71
	v_cvt_pk_bf16_f32 v5, v68, v69
	v_cvt_pk_bf16_f32 v24, v72, v73
	v_cvt_pk_bf16_f32 v25, v74, v75
	v_cvt_pk_bf16_f32 v26, v76, v77
	v_cvt_pk_bf16_f32 v27, v78, v79
	global_store_dwordx4 v[0:1], v[2:5], off
	global_store_dwordx4 v[0:1], v[24:27], off offset:16
	s_branch .LBB0_596

.LBB0_639:
	s_or_b64 exec, exec, s[34:35]
	s_waitcnt lgkmcnt(0)
	s_barrier
	s_and_saveexec_b64 s[8:9], s[6:7]
	s_cbranch_execz .LBB0_612
	v_add_u32_e32 v0, v10, v18
	v_cmp_gt_i32_e32 vcc, s94, v0
	s_and_b64 exec, exec, vcc
	s_cbranch_execz .LBB0_612
	ds_read2_b32 v[64:65], v26 offset1:65
	v_add_u32_e32 v1, 0x400, v26
	v_ashrrev_i32_e32 v9, 31, v8
	ds_read2_b32 v[66:67], v26 offset0:130 offset1:195
	ds_read2_b32 v[68:69], v1 offset0:4 offset1:69
	ds_read2_b32 v[70:71], v1 offset0:134 offset1:199
	v_add_u32_e32 v1, 0x800, v26
	ds_read2_b32 v[72:73], v1 offset0:8 offset1:73
	ds_read2_b32 v[74:75], v1 offset0:138 offset1:203
	v_add_u32_e32 v1, 0xc00, v26
	ds_read2_b32 v[76:77], v1 offset0:12 offset1:77
	ds_read2_b32 v[78:79], v1 offset0:142 offset1:207
	v_ashrrev_i32_e32 v1, 31, v0
	v_lshlrev_b64 v[0:1], 11, v[0:1]
	v_lshl_add_u64 v[0:1], s[14:15], 0, v[0:1]
	v_lshl_add_u64 v[0:1], v[8:9], 1, v[0:1]
	v_lshl_add_u64 v[0:1], v[0:1], 0, v[168:169]
	s_waitcnt lgkmcnt(0)
	v_cvt_pk_bf16_f32 v10, v64, v65
	v_cvt_pk_bf16_f32 v11, v66, v67
	v_cvt_pk_bf16_f32 v12, v68, v69
	v_cvt_pk_bf16_f32 v13, v70, v71
	v_cvt_pk_bf16_f32 v28, v72, v73
	v_cvt_pk_bf16_f32 v29, v74, v75
	v_cvt_pk_bf16_f32 v30, v76, v77
	v_cvt_pk_bf16_f32 v31, v78, v79
	global_store_dwordx4 v[0:1], v[10:13], off
	global_store_dwordx4 v[0:1], v[28:31], off offset:16
	s_branch .LBB0_612

.LBB0_655:
	s_or_b64 exec, exec, s[2:3]
	s_waitcnt lgkmcnt(0)
	s_barrier
	s_and_saveexec_b64 s[2:3], vcc
	s_cbranch_execz .LBB0_644
	v_add_u32_e32 v0, v12, v16
	v_cmp_gt_i32_e32 vcc, s92, v0
	s_and_b64 exec, exec, vcc
	s_cbranch_execz .LBB0_644
	ds_read2_b32 v[64:65], v21 offset1:65
	ds_read2_b32 v[66:67], v21 offset0:130 offset1:195
	v_add_u32_e32 v1, 0x400, v21
	ds_read2_b32 v[68:69], v1 offset0:134 offset1:199
	v_ashrrev_i32_e32 v11, 31, v10
	ds_read2_b32 v[70:71], v1 offset0:4 offset1:69
	v_add_u32_e32 v1, 0x800, v21
	ds_read2_b32 v[72:73], v1 offset0:8 offset1:73
	ds_read2_b32 v[74:75], v1 offset0:138 offset1:203
	v_add_u32_e32 v1, 0xc00, v21
	ds_read2_b32 v[76:77], v1 offset0:12 offset1:77
	ds_read2_b32 v[78:79], v1 offset0:142 offset1:207
	v_ashrrev_i32_e32 v1, 31, v0
	v_lshlrev_b64 v[0:1], 13, v[0:1]
	v_lshl_add_u64 v[0:1], s[8:9], 0, v[0:1]
	v_lshl_add_u64 v[0:1], v[10:11], 1, v[0:1]
	v_lshl_add_u64 v[0:1], v[0:1], 0, v[168:169]
	s_waitcnt lgkmcnt(0)
	v_cvt_pk_bf16_f32 v2, v64, v65
	v_cvt_pk_bf16_f32 v3, v66, v67
	v_cvt_pk_bf16_f32 v4, v70, v71
	v_cvt_pk_bf16_f32 v5, v68, v69
	v_cvt_pk_bf16_f32 v24, v72, v73
	v_cvt_pk_bf16_f32 v25, v74, v75
	v_cvt_pk_bf16_f32 v26, v76, v77
	v_cvt_pk_bf16_f32 v27, v78, v79
	global_store_dwordx4 v[0:1], v[2:5], off
	global_store_dwordx4 v[0:1], v[24:27], off offset:16
	s_branch .LBB0_644

.LBB0_660:
	s_or_b64 exec, exec, s[8:9]
	s_waitcnt lgkmcnt(0)
	s_barrier
	s_and_saveexec_b64 s[8:9], s[12:13]
	s_cbranch_execz .LBB0_662
	v_and_b32_e32 v1, 48, v1
	v_mul_u32_u24_e32 v3, 0x104, v1
	v_lshlrev_b32_e32 v4, 2, v2
	v_add3_u32 v12, s89, v3, v4
	v_ashrrev_i32_e32 v3, 31, v2
	v_lshlrev_b64 v[2:3], 7, v[2:3]
	v_lshl_add_u64 v[2:3], s[18:19], 0, v[2:3]
	v_lshlrev_b32_e32 v168, 1, v1
	v_lshl_add_u64 v[10:11], v[2:3], 0, v[168:169]
	ds_read2_b32 v[64:65], v12 offset1:65
	ds_read2_b32 v[66:67], v12 offset0:130 offset1:195
	v_add_u32_e32 v1, 0x400, v12
	ds_read2_b32 v[68:69], v1 offset0:134 offset1:199
	s_mov_b64 s[12:13], 0x1e20000
	ds_read2_b32 v[70:71], v1 offset0:4 offset1:69
	v_add_u32_e32 v1, 0x800, v12
	ds_read2_b32 v[72:73], v1 offset0:138 offset1:203
	ds_read2_b32 v[74:75], v1 offset0:8 offset1:73
	v_add_u32_e32 v1, 0xc00, v12
	ds_read2_b32 v[76:77], v1 offset0:142 offset1:207
	ds_read2_b32 v[78:79], v1 offset0:12 offset1:77
	v_ashrrev_i32_e32 v1, 31, v0
	v_lshl_add_u64 v[0:1], v[0:1], 1, v[10:11]
	v_lshl_add_u64 v[10:11], v[0:1], 0, s[12:13]
	v_add_co_u32_e32 v0, vcc, 0x1e20000, v0
	v_addc_co_u32_e32 v1, vcc, 0, v1, vcc
	s_waitcnt lgkmcnt(0)
	v_cvt_pk_bf16_f32 v2, v64, v65
	v_cvt_pk_bf16_f32 v3, v66, v67
	v_cvt_pk_bf16_f32 v4, v70, v71
	v_cvt_pk_bf16_f32 v5, v68, v69
	v_cvt_pk_bf16_f32 v6, v74, v75
	v_cvt_pk_bf16_f32 v7, v72, v73
	v_cvt_pk_bf16_f32 v8, v78, v79
	v_cvt_pk_bf16_f32 v9, v76, v77
	global_store_dwordx4 v[0:1], v[2:5], off
	global_store_dwordx4 v[10:11], v[6:9], off offset:16

.LBB0_664:
	s_or_b64 exec, exec, s[12:13]
	s_waitcnt lgkmcnt(0)
	s_barrier
	s_and_saveexec_b64 s[2:3], s[14:15]
	s_cbranch_execz .LBB0_666
	v_and_b32_e32 v1, 48, v1
	v_mul_u32_u24_e32 v3, 0x104, v1
	v_lshlrev_b32_e32 v4, 2, v2
	v_add3_u32 v12, s89, v3, v4
	v_ashrrev_i32_e32 v3, 31, v2
	v_lshlrev_b64 v[2:3], 7, v[2:3]
	v_lshl_add_u64 v[2:3], s[18:19], 0, v[2:3]
	v_lshlrev_b32_e32 v168, 1, v1
	v_lshl_add_u64 v[10:11], v[2:3], 0, v[168:169]
	ds_read2_b32 v[64:65], v12 offset1:65
	ds_read2_b32 v[66:67], v12 offset0:130 offset1:195
	v_add_u32_e32 v1, 0x400, v12
	ds_read2_b32 v[68:69], v1 offset0:134 offset1:199
	s_mov_b64 s[12:13], 0x1e28000
	ds_read2_b32 v[70:71], v1 offset0:4 offset1:69
	v_add_u32_e32 v1, 0x800, v12
	ds_read2_b32 v[72:73], v1 offset0:138 offset1:203
	ds_read2_b32 v[74:75], v1 offset0:8 offset1:73
	v_add_u32_e32 v1, 0xc00, v12
	ds_read2_b32 v[76:77], v1 offset0:142 offset1:207
	ds_read2_b32 v[78:79], v1 offset0:12 offset1:77
	v_ashrrev_i32_e32 v1, 31, v0
	v_lshl_add_u64 v[0:1], v[0:1], 1, v[10:11]
	v_lshl_add_u64 v[10:11], v[0:1], 0, s[12:13]
	v_add_co_u32_e32 v0, vcc, 0x1e28000, v0
	v_addc_co_u32_e32 v1, vcc, 0, v1, vcc
	s_waitcnt lgkmcnt(0)
	v_cvt_pk_bf16_f32 v2, v64, v65
	v_cvt_pk_bf16_f32 v3, v66, v67
	v_cvt_pk_bf16_f32 v4, v70, v71
	v_cvt_pk_bf16_f32 v5, v68, v69
	v_cvt_pk_bf16_f32 v6, v74, v75
	v_cvt_pk_bf16_f32 v7, v72, v73
	v_cvt_pk_bf16_f32 v8, v78, v79
	v_cvt_pk_bf16_f32 v9, v76, v77
	global_store_dwordx4 v[0:1], v[2:5], off
	global_store_dwordx4 v[10:11], v[6:9], off offset:16

.LBB0_668:
	s_or_b64 exec, exec, s[12:13]
	s_waitcnt lgkmcnt(0)
	s_barrier
	s_and_saveexec_b64 s[12:13], s[14:15]
	s_cbranch_execz .LBB0_670
	v_and_b32_e32 v1, 48, v1
	v_mul_u32_u24_e32 v3, 0x104, v1
	v_lshlrev_b32_e32 v4, 2, v2
	v_add3_u32 v12, s89, v3, v4
	v_ashrrev_i32_e32 v3, 31, v2
	v_lshlrev_b64 v[2:3], 7, v[2:3]
	v_lshl_add_u64 v[2:3], s[18:19], 0, v[2:3]
	v_lshlrev_b32_e32 v168, 1, v1
	v_lshl_add_u64 v[10:11], v[2:3], 0, v[168:169]
	ds_read2_b32 v[64:65], v12 offset1:65
	ds_read2_b32 v[66:67], v12 offset0:130 offset1:195
	v_add_u32_e32 v1, 0x400, v12
	ds_read2_b32 v[68:69], v1 offset0:134 offset1:199
	s_mov_b64 s[14:15], 0x1e22000
	ds_read2_b32 v[70:71], v1 offset0:4 offset1:69
	v_add_u32_e32 v1, 0x800, v12
	ds_read2_b32 v[72:73], v1 offset0:138 offset1:203
	ds_read2_b32 v[74:75], v1 offset0:8 offset1:73
	v_add_u32_e32 v1, 0xc00, v12
	ds_read2_b32 v[76:77], v1 offset0:142 offset1:207
	ds_read2_b32 v[78:79], v1 offset0:12 offset1:77
	v_ashrrev_i32_e32 v1, 31, v0
	v_lshl_add_u64 v[0:1], v[0:1], 1, v[10:11]
	v_lshl_add_u64 v[10:11], v[0:1], 0, s[14:15]
	v_add_co_u32_e32 v0, vcc, 0x1e22000, v0
	v_addc_co_u32_e32 v1, vcc, 0, v1, vcc
	s_waitcnt lgkmcnt(0)
	v_cvt_pk_bf16_f32 v2, v64, v65
	v_cvt_pk_bf16_f32 v3, v66, v67
	v_cvt_pk_bf16_f32 v4, v70, v71
	v_cvt_pk_bf16_f32 v5, v68, v69
	v_cvt_pk_bf16_f32 v6, v74, v75
	v_cvt_pk_bf16_f32 v7, v72, v73
	v_cvt_pk_bf16_f32 v8, v78, v79
	v_cvt_pk_bf16_f32 v9, v76, v77
	global_store_dwordx4 v[0:1], v[2:5], off
	global_store_dwordx4 v[10:11], v[6:9], off offset:16

.LBB0_672:
	s_or_b64 exec, exec, s[12:13]
	s_waitcnt lgkmcnt(0)
	s_barrier
	s_and_saveexec_b64 s[2:3], s[14:15]
	s_cbranch_execz .LBB0_674
	v_and_b32_e32 v1, 48, v1
	v_mul_u32_u24_e32 v3, 0x104, v1
	v_lshlrev_b32_e32 v4, 2, v2
	v_add3_u32 v12, s89, v3, v4
	v_ashrrev_i32_e32 v3, 31, v2
	v_lshlrev_b64 v[2:3], 7, v[2:3]
	v_lshl_add_u64 v[2:3], s[18:19], 0, v[2:3]
	v_lshlrev_b32_e32 v168, 1, v1
	v_lshl_add_u64 v[10:11], v[2:3], 0, v[168:169]
	ds_read2_b32 v[64:65], v12 offset1:65
	ds_read2_b32 v[66:67], v12 offset0:130 offset1:195
	v_add_u32_e32 v1, 0x400, v12
	ds_read2_b32 v[68:69], v1 offset0:134 offset1:199
	s_mov_b64 s[12:13], 0x1e2a000
	ds_read2_b32 v[70:71], v1 offset0:4 offset1:69
	v_add_u32_e32 v1, 0x800, v12
	ds_read2_b32 v[72:73], v1 offset0:138 offset1:203
	ds_read2_b32 v[74:75], v1 offset0:8 offset1:73
	v_add_u32_e32 v1, 0xc00, v12
	ds_read2_b32 v[76:77], v1 offset0:142 offset1:207
	ds_read2_b32 v[78:79], v1 offset0:12 offset1:77
	v_ashrrev_i32_e32 v1, 31, v0
	v_lshl_add_u64 v[0:1], v[0:1], 1, v[10:11]
	v_lshl_add_u64 v[10:11], v[0:1], 0, s[12:13]
	v_add_co_u32_e32 v0, vcc, 0x1e2a000, v0
	v_addc_co_u32_e32 v1, vcc, 0, v1, vcc
	s_waitcnt lgkmcnt(0)
	v_cvt_pk_bf16_f32 v2, v64, v65
	v_cvt_pk_bf16_f32 v3, v66, v67
	v_cvt_pk_bf16_f32 v4, v70, v71
	v_cvt_pk_bf16_f32 v5, v68, v69
	v_cvt_pk_bf16_f32 v6, v74, v75
	v_cvt_pk_bf16_f32 v7, v72, v73
	v_cvt_pk_bf16_f32 v8, v78, v79
	v_cvt_pk_bf16_f32 v9, v76, v77
	global_store_dwordx4 v[0:1], v[2:5], off
	global_store_dwordx4 v[10:11], v[6:9], off offset:16

.LBB0_676:
	s_or_b64 exec, exec, s[12:13]
	s_waitcnt lgkmcnt(0)
	s_barrier
	s_and_saveexec_b64 s[12:13], s[14:15]
	s_cbranch_execz .LBB0_678
	v_and_b32_e32 v1, 48, v1
	v_mul_u32_u24_e32 v3, 0x104, v1
	v_lshlrev_b32_e32 v4, 2, v2
	v_add3_u32 v12, s89, v3, v4
	v_ashrrev_i32_e32 v3, 31, v2
	v_lshlrev_b64 v[2:3], 7, v[2:3]
	v_lshl_add_u64 v[2:3], s[18:19], 0, v[2:3]
	v_lshlrev_b32_e32 v168, 1, v1
	v_lshl_add_u64 v[10:11], v[2:3], 0, v[168:169]
	ds_read2_b32 v[64:65], v12 offset1:65
	ds_read2_b32 v[66:67], v12 offset0:130 offset1:195
	v_add_u32_e32 v1, 0x400, v12
	ds_read2_b32 v[68:69], v1 offset0:134 offset1:199
	s_mov_b64 s[14:15], 0x1e24000
	ds_read2_b32 v[70:71], v1 offset0:4 offset1:69
	v_add_u32_e32 v1, 0x800, v12
	ds_read2_b32 v[72:73], v1 offset0:138 offset1:203
	ds_read2_b32 v[74:75], v1 offset0:8 offset1:73
	v_add_u32_e32 v1, 0xc00, v12
	ds_read2_b32 v[76:77], v1 offset0:142 offset1:207
	ds_read2_b32 v[78:79], v1 offset0:12 offset1:77
	v_ashrrev_i32_e32 v1, 31, v0
	v_lshl_add_u64 v[0:1], v[0:1], 1, v[10:11]
	v_lshl_add_u64 v[10:11], v[0:1], 0, s[14:15]
	v_add_co_u32_e32 v0, vcc, 0x1e24000, v0
	v_addc_co_u32_e32 v1, vcc, 0, v1, vcc
	s_waitcnt lgkmcnt(0)
	v_cvt_pk_bf16_f32 v2, v64, v65
	v_cvt_pk_bf16_f32 v3, v66, v67
	v_cvt_pk_bf16_f32 v4, v70, v71
	v_cvt_pk_bf16_f32 v5, v68, v69
	v_cvt_pk_bf16_f32 v6, v74, v75
	v_cvt_pk_bf16_f32 v7, v72, v73
	v_cvt_pk_bf16_f32 v8, v78, v79
	v_cvt_pk_bf16_f32 v9, v76, v77
	global_store_dwordx4 v[0:1], v[2:5], off
	global_store_dwordx4 v[10:11], v[6:9], off offset:16

.LBB0_680:
	s_or_b64 exec, exec, s[12:13]
	s_waitcnt lgkmcnt(0)
	s_barrier
	s_and_saveexec_b64 s[2:3], s[14:15]
	s_cbranch_execz .LBB0_682
	v_and_b32_e32 v1, 48, v1
	v_mul_u32_u24_e32 v3, 0x104, v1
	v_lshlrev_b32_e32 v4, 2, v2
	v_add3_u32 v12, s89, v3, v4
	v_ashrrev_i32_e32 v3, 31, v2
	v_lshlrev_b64 v[2:3], 7, v[2:3]
	v_lshl_add_u64 v[2:3], s[18:19], 0, v[2:3]
	v_lshlrev_b32_e32 v168, 1, v1
	v_lshl_add_u64 v[10:11], v[2:3], 0, v[168:169]
	ds_read2_b32 v[64:65], v12 offset1:65
	ds_read2_b32 v[66:67], v12 offset0:130 offset1:195
	v_add_u32_e32 v1, 0x400, v12
	ds_read2_b32 v[68:69], v1 offset0:134 offset1:199
	s_mov_b64 s[12:13], 0x1e2c000
	ds_read2_b32 v[70:71], v1 offset0:4 offset1:69
	v_add_u32_e32 v1, 0x800, v12
	ds_read2_b32 v[72:73], v1 offset0:138 offset1:203
	ds_read2_b32 v[74:75], v1 offset0:8 offset1:73
	v_add_u32_e32 v1, 0xc00, v12
	ds_read2_b32 v[76:77], v1 offset0:142 offset1:207
	ds_read2_b32 v[78:79], v1 offset0:12 offset1:77
	v_ashrrev_i32_e32 v1, 31, v0
	v_lshl_add_u64 v[0:1], v[0:1], 1, v[10:11]
	v_lshl_add_u64 v[10:11], v[0:1], 0, s[12:13]
	v_add_co_u32_e32 v0, vcc, 0x1e2c000, v0
	v_addc_co_u32_e32 v1, vcc, 0, v1, vcc
	s_waitcnt lgkmcnt(0)
	v_cvt_pk_bf16_f32 v2, v64, v65
	v_cvt_pk_bf16_f32 v3, v66, v67
	v_cvt_pk_bf16_f32 v4, v70, v71
	v_cvt_pk_bf16_f32 v5, v68, v69
	v_cvt_pk_bf16_f32 v6, v74, v75
	v_cvt_pk_bf16_f32 v7, v72, v73
	v_cvt_pk_bf16_f32 v8, v78, v79
	v_cvt_pk_bf16_f32 v9, v76, v77
	global_store_dwordx4 v[0:1], v[2:5], off
	global_store_dwordx4 v[10:11], v[6:9], off offset:16

.LBB0_684:
	s_or_b64 exec, exec, s[10:11]
	s_waitcnt lgkmcnt(0)
	s_barrier
	s_and_saveexec_b64 s[6:7], s[12:13]
	s_cbranch_execz .LBB0_686
	v_and_b32_e32 v1, 48, v1
	v_mul_u32_u24_e32 v3, 0x104, v1
	v_lshlrev_b32_e32 v4, 2, v2
	v_add3_u32 v12, s89, v3, v4
	v_ashrrev_i32_e32 v3, 31, v2
	v_lshlrev_b64 v[2:3], 7, v[2:3]
	v_lshl_add_u64 v[2:3], s[18:19], 0, v[2:3]
	v_lshlrev_b32_e32 v168, 1, v1
	v_lshl_add_u64 v[10:11], v[2:3], 0, v[168:169]
	ds_read2_b32 v[64:65], v12 offset1:65
	ds_read2_b32 v[66:67], v12 offset0:130 offset1:195
	v_add_u32_e32 v1, 0x400, v12
	ds_read2_b32 v[68:69], v1 offset0:134 offset1:199
	s_mov_b64 s[10:11], 0x1e26000
	ds_read2_b32 v[70:71], v1 offset0:4 offset1:69
	v_add_u32_e32 v1, 0x800, v12
	ds_read2_b32 v[72:73], v1 offset0:138 offset1:203
	ds_read2_b32 v[74:75], v1 offset0:8 offset1:73
	v_add_u32_e32 v1, 0xc00, v12
	ds_read2_b32 v[76:77], v1 offset0:142 offset1:207
	ds_read2_b32 v[78:79], v1 offset0:12 offset1:77
	v_ashrrev_i32_e32 v1, 31, v0
	v_lshl_add_u64 v[0:1], v[0:1], 1, v[10:11]
	v_lshl_add_u64 v[10:11], v[0:1], 0, s[10:11]
	v_add_co_u32_e32 v0, vcc, 0x1e26000, v0
	v_addc_co_u32_e32 v1, vcc, 0, v1, vcc
	s_waitcnt lgkmcnt(0)
	v_cvt_pk_bf16_f32 v2, v64, v65
	v_cvt_pk_bf16_f32 v3, v66, v67
	v_cvt_pk_bf16_f32 v4, v70, v71
	v_cvt_pk_bf16_f32 v5, v68, v69
	v_cvt_pk_bf16_f32 v6, v74, v75
	v_cvt_pk_bf16_f32 v7, v72, v73
	v_cvt_pk_bf16_f32 v8, v78, v79
	v_cvt_pk_bf16_f32 v9, v76, v77
	global_store_dwordx4 v[0:1], v[2:5], off
	global_store_dwordx4 v[10:11], v[6:9], off offset:16

.LBB0_688:
	s_or_b64 exec, exec, s[6:7]
	s_waitcnt lgkmcnt(0)
	s_barrier
	s_and_saveexec_b64 s[2:3], s[10:11]
	s_cbranch_execz .LBB0_690
	v_and_b32_e32 v1, 48, v1
	v_mul_u32_u24_e32 v3, 0x104, v1
	v_lshlrev_b32_e32 v4, 2, v2
	v_add3_u32 v12, s89, v3, v4
	v_ashrrev_i32_e32 v3, 31, v2
	v_lshlrev_b64 v[2:3], 7, v[2:3]
	v_lshl_add_u64 v[2:3], s[18:19], 0, v[2:3]
	v_lshlrev_b32_e32 v168, 1, v1
	v_lshl_add_u64 v[10:11], v[2:3], 0, v[168:169]
	ds_read2_b32 v[64:65], v12 offset1:65
	ds_read2_b32 v[66:67], v12 offset0:130 offset1:195
	v_add_u32_e32 v1, 0x400, v12
	ds_read2_b32 v[68:69], v1 offset0:134 offset1:199
	s_mov_b64 s[0:1], 0x1e2e000
	ds_read2_b32 v[70:71], v1 offset0:4 offset1:69
	v_add_u32_e32 v1, 0x800, v12
	ds_read2_b32 v[72:73], v1 offset0:138 offset1:203
	ds_read2_b32 v[74:75], v1 offset0:8 offset1:73
	v_add_u32_e32 v1, 0xc00, v12
	ds_read2_b32 v[76:77], v1 offset0:142 offset1:207
	ds_read2_b32 v[78:79], v1 offset0:12 offset1:77
	v_ashrrev_i32_e32 v1, 31, v0
	v_lshl_add_u64 v[0:1], v[0:1], 1, v[10:11]
	v_lshl_add_u64 v[10:11], v[0:1], 0, s[0:1]
	v_add_co_u32_e32 v0, vcc, 0x1e2e000, v0
	v_addc_co_u32_e32 v1, vcc, 0, v1, vcc
	s_waitcnt lgkmcnt(0)
	v_cvt_pk_bf16_f32 v2, v64, v65
	v_cvt_pk_bf16_f32 v3, v66, v67
	v_cvt_pk_bf16_f32 v4, v70, v71
	v_cvt_pk_bf16_f32 v5, v68, v69
	v_cvt_pk_bf16_f32 v6, v74, v75
	v_cvt_pk_bf16_f32 v7, v72, v73
	v_cvt_pk_bf16_f32 v8, v78, v79
	v_cvt_pk_bf16_f32 v9, v76, v77
	global_store_dwordx4 v[0:1], v[2:5], off
	global_store_dwordx4 v[10:11], v[6:9], off offset:16

.LBB0_1395:
	s_or_b64 exec, exec, s[12:13]
	s_waitcnt lgkmcnt(0)
	s_barrier
	s_and_saveexec_b64 s[8:9], s[6:7]
	s_cbranch_execz .LBB0_1368
	v_add_u32_e32 v0, v10, v18
	v_cmp_gt_i32_e32 vcc, s70, v0
	s_and_b64 exec, exec, vcc
	s_cbranch_execz .LBB0_1368
	v_add_u32_e32 v1, 0x400, v26
	ds_read2_b32 v[64:65], v26 offset1:65
	ds_read2_b32 v[66:67], v26 offset0:130 offset1:195
	ds_read2_b32 v[68:69], v1 offset0:4 offset1:69
	v_ashrrev_i32_e32 v9, 31, v8
	ds_read2_b32 v[70:71], v1 offset0:134 offset1:199
	v_add_u32_e32 v1, 0x800, v26
	ds_read2_b32 v[72:73], v1 offset0:8 offset1:73
	ds_read2_b32 v[74:75], v1 offset0:138 offset1:203
	v_add_u32_e32 v1, 0xc00, v26
	ds_read2_b32 v[76:77], v1 offset0:12 offset1:77
	ds_read2_b32 v[78:79], v1 offset0:142 offset1:207
	v_ashrrev_i32_e32 v1, 31, v0
	v_lshlrev_b64 v[0:1], 11, v[0:1]
	v_lshl_add_u64 v[0:1], s[2:3], 0, v[0:1]
	v_lshl_add_u64 v[0:1], v[8:9], 1, v[0:1]
	v_lshl_add_u64 v[0:1], v[0:1], 0, v[168:169]
	s_waitcnt lgkmcnt(0)
	v_cvt_pk_bf16_f32 v10, v64, v65
	v_cvt_pk_bf16_f32 v11, v66, v67
	v_cvt_pk_bf16_f32 v12, v68, v69
	v_cvt_pk_bf16_f32 v13, v70, v71
	v_cvt_pk_bf16_f32 v28, v72, v73
	v_cvt_pk_bf16_f32 v29, v74, v75
	v_cvt_pk_bf16_f32 v30, v76, v77
	v_cvt_pk_bf16_f32 v31, v78, v79
	global_store_dwordx4 v[0:1], v[10:13], off
	global_store_dwordx4 v[0:1], v[28:31], off offset:16
	s_branch .LBB0_1368

.LBB0_1427:
	s_or_b64 exec, exec, s[12:13]
	s_waitcnt lgkmcnt(0)
	s_barrier
	s_and_saveexec_b64 s[8:9], s[6:7]
	s_cbranch_execz .LBB0_1400
	v_add_u32_e32 v0, v10, v18
	v_cmp_gt_i32_e32 vcc, s69, v0
	s_and_b64 exec, exec, vcc
	s_cbranch_execz .LBB0_1400
	v_add_u32_e32 v1, 0x400, v26
	ds_read2_b32 v[64:65], v26 offset1:65
	ds_read2_b32 v[66:67], v26 offset0:130 offset1:195
	ds_read2_b32 v[68:69], v1 offset0:4 offset1:69
	v_ashrrev_i32_e32 v9, 31, v8
	ds_read2_b32 v[70:71], v1 offset0:134 offset1:199
	v_add_u32_e32 v1, 0x800, v26
	ds_read2_b32 v[72:73], v1 offset0:8 offset1:73
	ds_read2_b32 v[74:75], v1 offset0:138 offset1:203
	v_add_u32_e32 v1, 0xc00, v26
	ds_read2_b32 v[76:77], v1 offset0:12 offset1:77
	ds_read2_b32 v[78:79], v1 offset0:142 offset1:207
	v_ashrrev_i32_e32 v1, 31, v0
	v_lshlrev_b64 v[0:1], 11, v[0:1]
	v_lshl_add_u64 v[0:1], s[2:3], 0, v[0:1]
	v_lshl_add_u64 v[0:1], v[8:9], 1, v[0:1]
	v_lshl_add_u64 v[0:1], v[0:1], 0, v[168:169]
	s_waitcnt lgkmcnt(0)
	v_cvt_pk_bf16_f32 v10, v64, v65
	v_cvt_pk_bf16_f32 v11, v66, v67
	v_cvt_pk_bf16_f32 v12, v68, v69
	v_cvt_pk_bf16_f32 v13, v70, v71
	v_cvt_pk_bf16_f32 v28, v72, v73
	v_cvt_pk_bf16_f32 v29, v74, v75
	v_cvt_pk_bf16_f32 v30, v76, v77
	v_cvt_pk_bf16_f32 v31, v78, v79
	global_store_dwordx4 v[0:1], v[10:13], off
	global_store_dwordx4 v[0:1], v[28:31], off offset:16
	s_branch .LBB0_1400

.LBB0_1455:
	s_or_b64 exec, exec, s[22:23]
	s_xor_b64 s[22:23], s[12:13], -1
	s_waitcnt lgkmcnt(0)
	s_barrier
	s_and_saveexec_b64 s[12:13], s[22:23]
	s_cbranch_execz .LBB0_1432
	ds_read2_b32 v[64:65], v20 offset1:65
	ds_read2_b32 v[66:67], v20 offset0:130 offset1:195
	v_add_u32_e32 v11, 0x400, v20
	ds_read2_b32 v[68:69], v11 offset0:4 offset1:69
	v_cndmask_b32_e64 v26, v10, 0, s[10:11]
	v_add_u32_e32 v3, 0x800, v20
	ds_read2_b32 v[70:71], v11 offset0:134 offset1:199
	ds_read2_b32 v[72:73], v3 offset0:8 offset1:73
	ds_read2_b32 v[74:75], v3 offset0:138 offset1:203
	v_add_u32_e32 v3, 0xc00, v20
	ds_read2_b32 v[76:77], v3 offset0:12 offset1:77
	ds_read2_b32 v[78:79], v3 offset0:142 offset1:207
	v_ashrrev_i32_e32 v27, 31, v26
	v_lshl_add_u64 v[14:15], v[26:27], 1, v[8:9]
	s_waitcnt lgkmcnt(0)
	v_cvt_pk_bf16_f32 v0, v64, v65
	v_cvt_pk_bf16_f32 v1, v66, v67
	v_cvt_pk_bf16_f32 v2, v68, v69
	v_cvt_pk_bf16_f32 v3, v70, v71
	v_cvt_pk_bf16_f32 v22, v72, v73
	v_cvt_pk_bf16_f32 v23, v74, v75
	v_cvt_pk_bf16_f32 v24, v76, v77
	v_cvt_pk_bf16_f32 v25, v78, v79
	global_store_dwordx4 v[14:15], v[0:3], off
	global_store_dwordx4 v[14:15], v[22:25], off offset:16
	s_branch .LBB0_1432

.LBB0_1483:
	s_or_b64 exec, exec, s[2:3]
	s_xor_b64 s[12:13], s[12:13], -1
	s_waitcnt lgkmcnt(0)
	s_barrier
	s_and_saveexec_b64 s[2:3], s[12:13]
	s_cbranch_execz .LBB0_1460
	ds_read2_b32 v[64:65], v20 offset1:65
	ds_read2_b32 v[66:67], v20 offset0:130 offset1:195
	v_add_u32_e32 v11, 0x400, v20
	ds_read2_b32 v[68:69], v11 offset0:4 offset1:69
	v_cndmask_b32_e64 v26, v10, 0, s[10:11]
	v_add_u32_e32 v3, 0x800, v20
	ds_read2_b32 v[70:71], v11 offset0:134 offset1:199
	ds_read2_b32 v[72:73], v3 offset0:8 offset1:73
	ds_read2_b32 v[74:75], v3 offset0:138 offset1:203
	v_add_u32_e32 v3, 0xc00, v20
	ds_read2_b32 v[76:77], v3 offset0:12 offset1:77
	ds_read2_b32 v[78:79], v3 offset0:142 offset1:207
	v_ashrrev_i32_e32 v27, 31, v26
	v_lshl_add_u64 v[14:15], v[26:27], 1, v[8:9]
	s_waitcnt lgkmcnt(0)
	v_cvt_pk_bf16_f32 v0, v64, v65
	v_cvt_pk_bf16_f32 v1, v66, v67
	v_cvt_pk_bf16_f32 v2, v68, v69
	v_cvt_pk_bf16_f32 v3, v70, v71
	v_cvt_pk_bf16_f32 v22, v72, v73
	v_cvt_pk_bf16_f32 v23, v74, v75
	v_cvt_pk_bf16_f32 v24, v76, v77
	v_cvt_pk_bf16_f32 v25, v78, v79
	global_store_dwordx4 v[14:15], v[0:3], off
	global_store_dwordx4 v[14:15], v[22:25], off offset:16
	s_branch .LBB0_1460

.LBB0_1514:
	s_or_b64 exec, exec, s[20:21]
	s_waitcnt lgkmcnt(0)
	s_barrier
	s_and_saveexec_b64 s[10:11], s[8:9]
	s_cbranch_execz .LBB0_1487
	v_add_u32_e32 v0, v10, v18
	v_cmp_gt_i32_e32 vcc, s70, v0
	s_and_b64 exec, exec, vcc
	s_cbranch_execz .LBB0_1487
	v_add_u32_e32 v1, 0x400, v26
	ds_read2_b32 v[64:65], v26 offset1:65
	ds_read2_b32 v[66:67], v26 offset0:130 offset1:195
	ds_read2_b32 v[68:69], v1 offset0:4 offset1:69
	v_ashrrev_i32_e32 v9, 31, v8
	ds_read2_b32 v[70:71], v1 offset0:134 offset1:199
	v_add_u32_e32 v1, 0x800, v26
	ds_read2_b32 v[72:73], v1 offset0:8 offset1:73
	ds_read2_b32 v[74:75], v1 offset0:138 offset1:203
	v_add_u32_e32 v1, 0xc00, v26
	ds_read2_b32 v[76:77], v1 offset0:12 offset1:77
	ds_read2_b32 v[78:79], v1 offset0:142 offset1:207
	v_ashrrev_i32_e32 v1, 31, v0
	v_lshlrev_b64 v[0:1], 11, v[0:1]
	v_lshl_add_u64 v[0:1], s[2:3], 0, v[0:1]
	v_lshl_add_u64 v[0:1], v[8:9], 1, v[0:1]
	v_lshl_add_u64 v[0:1], v[0:1], 0, v[168:169]
	s_waitcnt lgkmcnt(0)
	v_cvt_pk_bf16_f32 v10, v64, v65
	v_cvt_pk_bf16_f32 v11, v66, v67
	v_cvt_pk_bf16_f32 v12, v68, v69
	v_cvt_pk_bf16_f32 v13, v70, v71
	v_cvt_pk_bf16_f32 v28, v72, v73
	v_cvt_pk_bf16_f32 v29, v74, v75
	v_cvt_pk_bf16_f32 v30, v76, v77
	v_cvt_pk_bf16_f32 v31, v78, v79
	global_store_dwordx4 v[0:1], v[10:13], off
	global_store_dwordx4 v[0:1], v[28:31], off offset:16
	s_branch .LBB0_1487

.LBB0_1578:
	s_or_b64 exec, exec, s[20:21]
	s_waitcnt lgkmcnt(0)
	s_barrier
	s_and_saveexec_b64 s[12:13], s[10:11]
	s_cbranch_execz .LBB0_1551
	v_add_u32_e32 v0, v10, v18
	v_cmp_gt_i32_e32 vcc, s69, v0
	s_and_b64 exec, exec, vcc
	s_cbranch_execz .LBB0_1551
	v_add_u32_e32 v1, 0x400, v26
	ds_read2_b32 v[64:65], v26 offset1:65
	ds_read2_b32 v[66:67], v26 offset0:130 offset1:195
	ds_read2_b32 v[68:69], v1 offset0:4 offset1:69
	v_ashrrev_i32_e32 v9, 31, v8
	ds_read2_b32 v[70:71], v1 offset0:134 offset1:199
	v_add_u32_e32 v1, 0x800, v26
	ds_read2_b32 v[72:73], v1 offset0:8 offset1:73
	ds_read2_b32 v[74:75], v1 offset0:138 offset1:203
	v_add_u32_e32 v1, 0xc00, v26
	ds_read2_b32 v[76:77], v1 offset0:12 offset1:77
	ds_read2_b32 v[78:79], v1 offset0:142 offset1:207
	v_ashrrev_i32_e32 v1, 31, v0
	v_lshlrev_b64 v[0:1], 11, v[0:1]
	v_lshl_add_u64 v[0:1], s[2:3], 0, v[0:1]
	v_lshl_add_u64 v[0:1], v[8:9], 1, v[0:1]
	v_lshl_add_u64 v[0:1], v[0:1], 0, v[168:169]
	s_waitcnt lgkmcnt(0)
	v_cvt_pk_bf16_f32 v10, v64, v65
	v_cvt_pk_bf16_f32 v11, v66, v67
	v_cvt_pk_bf16_f32 v12, v68, v69
	v_cvt_pk_bf16_f32 v13, v70, v71
	v_cvt_pk_bf16_f32 v28, v72, v73
	v_cvt_pk_bf16_f32 v29, v74, v75
	v_cvt_pk_bf16_f32 v30, v76, v77
	v_cvt_pk_bf16_f32 v31, v78, v79
	global_store_dwordx4 v[0:1], v[10:13], off
	global_store_dwordx4 v[0:1], v[28:31], off offset:16
	s_branch .LBB0_1551

.LBB0_1642:
	s_or_b64 exec, exec, s[20:21]
	s_waitcnt lgkmcnt(0)
	s_barrier
	s_and_saveexec_b64 s[12:13], s[10:11]
	s_cbranch_execz .LBB0_1615
	v_add_u32_e32 v0, v10, v18
	v_cmp_gt_i32_e32 vcc, s70, v0
	s_and_b64 exec, exec, vcc
	s_cbranch_execz .LBB0_1615
	v_add_u32_e32 v1, 0x400, v26
	ds_read2_b32 v[64:65], v26 offset1:65
	ds_read2_b32 v[66:67], v26 offset0:130 offset1:195
	ds_read2_b32 v[68:69], v1 offset0:4 offset1:69
	v_ashrrev_i32_e32 v9, 31, v8
	ds_read2_b32 v[70:71], v1 offset0:134 offset1:199
	v_add_u32_e32 v1, 0x800, v26
	ds_read2_b32 v[72:73], v1 offset0:8 offset1:73
	ds_read2_b32 v[74:75], v1 offset0:138 offset1:203
	v_add_u32_e32 v1, 0xc00, v26
	ds_read2_b32 v[76:77], v1 offset0:12 offset1:77
	ds_read2_b32 v[78:79], v1 offset0:142 offset1:207
	v_ashrrev_i32_e32 v1, 31, v0
	v_lshlrev_b64 v[0:1], 11, v[0:1]
	v_lshl_add_u64 v[0:1], s[2:3], 0, v[0:1]
	v_lshl_add_u64 v[0:1], v[8:9], 1, v[0:1]
	v_lshl_add_u64 v[0:1], v[0:1], 0, v[168:169]
	s_waitcnt lgkmcnt(0)
	v_cvt_pk_bf16_f32 v10, v64, v65
	v_cvt_pk_bf16_f32 v11, v66, v67
	v_cvt_pk_bf16_f32 v12, v68, v69
	v_cvt_pk_bf16_f32 v13, v70, v71
	v_cvt_pk_bf16_f32 v28, v72, v73
	v_cvt_pk_bf16_f32 v29, v74, v75
	v_cvt_pk_bf16_f32 v30, v76, v77
	v_cvt_pk_bf16_f32 v31, v78, v79
	global_store_dwordx4 v[0:1], v[10:13], off
	global_store_dwordx4 v[0:1], v[28:31], off offset:16
	s_branch .LBB0_1615

.LBB0_1674:
	s_or_b64 exec, exec, s[18:19]
	s_waitcnt lgkmcnt(0)
	s_barrier
	s_and_saveexec_b64 s[12:13], s[10:11]
	s_cbranch_execz .LBB0_1647
	v_add_u32_e32 v0, v10, v18
	v_cmp_gt_i32_e32 vcc, s70, v0
	s_and_b64 exec, exec, vcc
	s_cbranch_execz .LBB0_1647
	v_add_u32_e32 v1, 0x400, v26
	ds_read2_b32 v[64:65], v26 offset1:65
	ds_read2_b32 v[66:67], v26 offset0:130 offset1:195
	ds_read2_b32 v[68:69], v1 offset0:4 offset1:69
	v_ashrrev_i32_e32 v9, 31, v8
	ds_read2_b32 v[70:71], v1 offset0:134 offset1:199
	v_add_u32_e32 v1, 0x800, v26
	ds_read2_b32 v[72:73], v1 offset0:8 offset1:73
	ds_read2_b32 v[74:75], v1 offset0:138 offset1:203
	v_add_u32_e32 v1, 0xc00, v26
	ds_read2_b32 v[76:77], v1 offset0:12 offset1:77
	ds_read2_b32 v[78:79], v1 offset0:142 offset1:207
	v_ashrrev_i32_e32 v1, 31, v0
	v_lshlrev_b64 v[0:1], 11, v[0:1]
	v_lshl_add_u64 v[0:1], s[2:3], 0, v[0:1]
	v_lshl_add_u64 v[0:1], v[8:9], 1, v[0:1]
	v_lshl_add_u64 v[0:1], v[0:1], 0, v[168:169]
	s_waitcnt lgkmcnt(0)
	v_cvt_pk_bf16_f32 v10, v64, v65
	v_cvt_pk_bf16_f32 v11, v66, v67
	v_cvt_pk_bf16_f32 v12, v68, v69
	v_cvt_pk_bf16_f32 v13, v70, v71
	v_cvt_pk_bf16_f32 v28, v72, v73
	v_cvt_pk_bf16_f32 v29, v74, v75
	v_cvt_pk_bf16_f32 v30, v76, v77
	v_cvt_pk_bf16_f32 v31, v78, v79
	global_store_dwordx4 v[0:1], v[10:13], off
	global_store_dwordx4 v[0:1], v[28:31], off offset:16
	s_branch .LBB0_1647

.LBB0_1709:
	s_or_b64 exec, exec, s[18:19]
	s_waitcnt lgkmcnt(0)
	s_barrier
	s_and_saveexec_b64 s[12:13], s[10:11]
	s_cbranch_execz .LBB0_1682
	v_add_u32_e32 v0, v10, v18
	v_cmp_gt_i32_e32 vcc, s76, v0
	s_and_b64 exec, exec, vcc
	s_cbranch_execz .LBB0_1682
	v_add_u32_e32 v1, 0x400, v26
	ds_read2_b32 v[64:65], v26 offset1:65
	ds_read2_b32 v[66:67], v26 offset0:130 offset1:195
	ds_read2_b32 v[68:69], v1 offset0:4 offset1:69
	v_ashrrev_i32_e32 v9, 31, v8
	ds_read2_b32 v[70:71], v1 offset0:134 offset1:199
	v_add_u32_e32 v1, 0x800, v26
	ds_read2_b32 v[72:73], v1 offset0:8 offset1:73
	ds_read2_b32 v[74:75], v1 offset0:138 offset1:203
	v_add_u32_e32 v1, 0xc00, v26
	ds_read2_b32 v[76:77], v1 offset0:12 offset1:77
	ds_read2_b32 v[78:79], v1 offset0:142 offset1:207
	v_ashrrev_i32_e32 v1, 31, v0
	v_lshlrev_b64 v[0:1], 9, v[0:1]
	v_lshl_add_u64 v[0:1], s[4:5], 0, v[0:1]
	v_lshl_add_u64 v[0:1], v[8:9], 1, v[0:1]
	v_lshl_add_u64 v[0:1], v[0:1], 0, v[168:169]
	s_waitcnt lgkmcnt(0)
	v_cvt_pk_bf16_f32 v10, v64, v65
	v_cvt_pk_bf16_f32 v11, v66, v67
	v_cvt_pk_bf16_f32 v12, v68, v69
	v_cvt_pk_bf16_f32 v13, v70, v71
	v_cvt_pk_bf16_f32 v28, v72, v73
	v_cvt_pk_bf16_f32 v29, v74, v75
	v_cvt_pk_bf16_f32 v30, v76, v77
	v_cvt_pk_bf16_f32 v31, v78, v79
	global_store_dwordx4 v[0:1], v[10:13], off
	global_store_dwordx4 v[0:1], v[28:31], off offset:16
	s_branch .LBB0_1682

.LBB0_1741:
	s_or_b64 exec, exec, s[16:17]
	s_waitcnt lgkmcnt(0)
	s_barrier
	s_and_saveexec_b64 s[10:11], s[8:9]
	s_cbranch_execz .LBB0_1714
	v_add_u32_e32 v0, v10, v18
	v_cmp_gt_i32_e32 vcc, s92, v0
	s_and_b64 exec, exec, vcc
	s_cbranch_execz .LBB0_1714
	v_add_u32_e32 v1, 0x400, v26
	ds_read2_b32 v[64:65], v26 offset1:65
	ds_read2_b32 v[66:67], v26 offset0:130 offset1:195
	ds_read2_b32 v[68:69], v1 offset0:4 offset1:69
	v_ashrrev_i32_e32 v9, 31, v8
	ds_read2_b32 v[70:71], v1 offset0:134 offset1:199
	v_add_u32_e32 v1, 0x800, v26
	ds_read2_b32 v[72:73], v1 offset0:8 offset1:73
	ds_read2_b32 v[74:75], v1 offset0:138 offset1:203
	v_add_u32_e32 v1, 0xc00, v26
	ds_read2_b32 v[76:77], v1 offset0:12 offset1:77
	ds_read2_b32 v[78:79], v1 offset0:142 offset1:207
	v_ashrrev_i32_e32 v1, 31, v0
	v_lshlrev_b64 v[0:1], 8, v[0:1]
	v_lshl_add_u64 v[0:1], s[4:5], 0, v[0:1]
	v_lshl_add_u64 v[0:1], v[8:9], 1, v[0:1]
	v_lshl_add_u64 v[0:1], v[0:1], 0, v[168:169]
	s_waitcnt lgkmcnt(0)
	v_cvt_pk_bf16_f32 v10, v64, v65
	v_cvt_pk_bf16_f32 v11, v66, v67
	v_cvt_pk_bf16_f32 v12, v68, v69
	v_cvt_pk_bf16_f32 v13, v70, v71
	v_cvt_pk_bf16_f32 v28, v72, v73
	v_cvt_pk_bf16_f32 v29, v74, v75
	v_cvt_pk_bf16_f32 v30, v76, v77
	v_cvt_pk_bf16_f32 v31, v78, v79
	global_store_dwordx4 v[0:1], v[10:13], off
	global_store_dwordx4 v[0:1], v[28:31], off offset:16
	s_branch .LBB0_1714

.LBB0_1773:
	s_or_b64 exec, exec, s[18:19]
	s_waitcnt lgkmcnt(0)
	s_barrier
	s_and_saveexec_b64 s[10:11], s[8:9]
	s_cbranch_execz .LBB0_1746
	v_add_u32_e32 v0, v10, v18
	v_cmp_gt_i32_e32 vcc, s92, v0
	s_and_b64 exec, exec, vcc
	s_cbranch_execz .LBB0_1746
	v_add_u32_e32 v1, 0x400, v26
	ds_read2_b32 v[64:65], v26 offset1:65
	ds_read2_b32 v[66:67], v26 offset0:130 offset1:195
	ds_read2_b32 v[68:69], v1 offset0:4 offset1:69
	v_ashrrev_i32_e32 v9, 31, v8
	ds_read2_b32 v[70:71], v1 offset0:134 offset1:199
	v_add_u32_e32 v1, 0x800, v26
	ds_read2_b32 v[72:73], v1 offset0:8 offset1:73
	ds_read2_b32 v[74:75], v1 offset0:138 offset1:203
	v_add_u32_e32 v1, 0xc00, v26
	ds_read2_b32 v[76:77], v1 offset0:12 offset1:77
	ds_read2_b32 v[78:79], v1 offset0:142 offset1:207
	v_ashrrev_i32_e32 v1, 31, v0
	v_lshlrev_b64 v[0:1], 11, v[0:1]
	v_lshl_add_u64 v[0:1], s[4:5], 0, v[0:1]
	v_lshl_add_u64 v[0:1], v[8:9], 1, v[0:1]
	v_lshl_add_u64 v[0:1], v[0:1], 0, v[168:169]
	s_waitcnt lgkmcnt(0)
	v_cvt_pk_bf16_f32 v10, v64, v65
	v_cvt_pk_bf16_f32 v11, v66, v67
	v_cvt_pk_bf16_f32 v12, v68, v69
	v_cvt_pk_bf16_f32 v13, v70, v71
	v_cvt_pk_bf16_f32 v28, v72, v73
	v_cvt_pk_bf16_f32 v29, v74, v75
	v_cvt_pk_bf16_f32 v30, v76, v77
	v_cvt_pk_bf16_f32 v31, v78, v79
	global_store_dwordx4 v[0:1], v[10:13], off
	global_store_dwordx4 v[0:1], v[28:31], off offset:16
	s_branch .LBB0_1746

.LBB0_1837:
	s_or_b64 exec, exec, s[2:3]
	s_waitcnt lgkmcnt(0)
	s_barrier
	s_and_saveexec_b64 s[2:3], s[6:7]
	s_cbranch_execz .LBB0_1810
	v_add_u32_e32 v0, v10, v18
	v_cmp_gt_i32_e32 vcc, s92, v0
	s_and_b64 exec, exec, vcc
	s_cbranch_execz .LBB0_1810
	v_add_u32_e32 v1, 0x400, v26
	ds_read2_b32 v[64:65], v26 offset1:65
	ds_read2_b32 v[66:67], v26 offset0:130 offset1:195
	ds_read2_b32 v[68:69], v1 offset0:4 offset1:69
	v_ashrrev_i32_e32 v9, 31, v8
	ds_read2_b32 v[70:71], v1 offset0:134 offset1:199
	v_add_u32_e32 v1, 0x800, v26
	ds_read2_b32 v[72:73], v1 offset0:8 offset1:73
	ds_read2_b32 v[74:75], v1 offset0:138 offset1:203
	v_add_u32_e32 v1, 0xc00, v26
	ds_read2_b32 v[76:77], v1 offset0:12 offset1:77
	ds_read2_b32 v[78:79], v1 offset0:142 offset1:207
	v_ashrrev_i32_e32 v1, 31, v0
	v_lshlrev_b64 v[0:1], 11, v[0:1]
	v_lshl_add_u64 v[0:1], s[4:5], 0, v[0:1]
	v_lshl_add_u64 v[0:1], v[8:9], 1, v[0:1]
	v_lshl_add_u64 v[0:1], v[0:1], 0, v[168:169]
	s_waitcnt lgkmcnt(0)
	v_cvt_pk_bf16_f32 v10, v64, v65
	v_cvt_pk_bf16_f32 v11, v66, v67
	v_cvt_pk_bf16_f32 v12, v68, v69
	v_cvt_pk_bf16_f32 v13, v70, v71
	v_cvt_pk_bf16_f32 v28, v72, v73
	v_cvt_pk_bf16_f32 v29, v74, v75
	v_cvt_pk_bf16_f32 v30, v76, v77
	v_cvt_pk_bf16_f32 v31, v78, v79
	global_store_dwordx4 v[0:1], v[10:13], off
	global_store_dwordx4 v[0:1], v[28:31], off offset:16
	s_branch .LBB0_1810

.LBB0_1869:
	s_or_b64 exec, exec, s[16:17]
	s_waitcnt lgkmcnt(0)
	s_barrier
	s_and_saveexec_b64 s[8:9], s[6:7]
	s_cbranch_execz .LBB0_1842
	v_add_u32_e32 v0, v10, v18
	v_cmp_gt_i32_e32 vcc, s92, v0
	s_and_b64 exec, exec, vcc
	s_cbranch_execz .LBB0_1842
	v_add_u32_e32 v1, 0x400, v26
	ds_read2_b32 v[64:65], v26 offset1:65
	ds_read2_b32 v[66:67], v26 offset0:130 offset1:195
	ds_read2_b32 v[68:69], v1 offset0:4 offset1:69
	v_ashrrev_i32_e32 v9, 31, v8
	ds_read2_b32 v[70:71], v1 offset0:134 offset1:199
	v_add_u32_e32 v1, 0x800, v26
	ds_read2_b32 v[72:73], v1 offset0:8 offset1:73
	ds_read2_b32 v[74:75], v1 offset0:138 offset1:203
	v_add_u32_e32 v1, 0xc00, v26
	ds_read2_b32 v[76:77], v1 offset0:12 offset1:77
	ds_read2_b32 v[78:79], v1 offset0:142 offset1:207
	v_ashrrev_i32_e32 v1, 31, v0
	v_lshlrev_b64 v[0:1], 11, v[0:1]
	v_lshl_add_u64 v[0:1], s[12:13], 0, v[0:1]
	v_lshl_add_u64 v[0:1], v[8:9], 1, v[0:1]
	v_lshl_add_u64 v[0:1], v[0:1], 0, v[168:169]
	s_waitcnt lgkmcnt(0)
	v_cvt_pk_bf16_f32 v10, v64, v65
	v_cvt_pk_bf16_f32 v11, v66, v67
	v_cvt_pk_bf16_f32 v12, v68, v69
	v_cvt_pk_bf16_f32 v13, v70, v71
	v_cvt_pk_bf16_f32 v28, v72, v73
	v_cvt_pk_bf16_f32 v29, v74, v75
	v_cvt_pk_bf16_f32 v30, v76, v77
	v_cvt_pk_bf16_f32 v31, v78, v79
	global_store_dwordx4 v[0:1], v[10:13], off
	global_store_dwordx4 v[0:1], v[28:31], off offset:16
	s_branch .LBB0_1842

.LBB0_1901:
	s_or_b64 exec, exec, s[16:17]
	s_waitcnt lgkmcnt(0)
	s_barrier
	s_and_saveexec_b64 s[10:11], s[8:9]
	s_cbranch_execz .LBB0_1874
	v_add_u32_e32 v0, v10, v18
	v_cmp_gt_i32_e32 vcc, s92, v0
	s_and_b64 exec, exec, vcc
	s_cbranch_execz .LBB0_1874
	v_add_u32_e32 v1, 0x400, v26
	ds_read2_b32 v[64:65], v26 offset1:65
	ds_read2_b32 v[66:67], v26 offset0:130 offset1:195
	ds_read2_b32 v[68:69], v1 offset0:4 offset1:69
	v_ashrrev_i32_e32 v9, 31, v8
	ds_read2_b32 v[70:71], v1 offset0:134 offset1:199
	v_add_u32_e32 v1, 0x800, v26
	ds_read2_b32 v[72:73], v1 offset0:8 offset1:73
	ds_read2_b32 v[74:75], v1 offset0:138 offset1:203
	v_add_u32_e32 v1, 0xc00, v26
	ds_read2_b32 v[76:77], v1 offset0:12 offset1:77
	ds_read2_b32 v[78:79], v1 offset0:142 offset1:207
	v_ashrrev_i32_e32 v1, 31, v0
	v_lshlrev_b64 v[0:1], 11, v[0:1]
	v_lshl_add_u64 v[0:1], s[4:5], 0, v[0:1]
	v_lshl_add_u64 v[0:1], v[8:9], 1, v[0:1]
	v_lshl_add_u64 v[0:1], v[0:1], 0, v[168:169]
	s_waitcnt lgkmcnt(0)
	v_cvt_pk_bf16_f32 v10, v64, v65
	v_cvt_pk_bf16_f32 v11, v66, v67
	v_cvt_pk_bf16_f32 v12, v68, v69
	v_cvt_pk_bf16_f32 v13, v70, v71
	v_cvt_pk_bf16_f32 v28, v72, v73
	v_cvt_pk_bf16_f32 v29, v74, v75
	v_cvt_pk_bf16_f32 v30, v76, v77
	v_cvt_pk_bf16_f32 v31, v78, v79
	global_store_dwordx4 v[0:1], v[10:13], off
	global_store_dwordx4 v[0:1], v[28:31], off offset:16
	s_branch .LBB0_1874

.LBB0_1917:
	s_or_b64 exec, exec, s[4:5]
	s_waitcnt lgkmcnt(0)
	s_barrier
	s_and_saveexec_b64 s[4:5], vcc
	s_cbranch_execz .LBB0_1906
	v_add_u32_e32 v0, v12, v16
	v_cmp_gt_i32_e32 vcc, s92, v0
	s_and_b64 exec, exec, vcc
	s_cbranch_execz .LBB0_1906
	v_add_u32_e32 v1, 0x400, v21
	ds_read2_b32 v[64:65], v21 offset1:65
	ds_read2_b32 v[66:67], v21 offset0:130 offset1:195
	ds_read2_b32 v[68:69], v1 offset0:4 offset1:69
	v_ashrrev_i32_e32 v11, 31, v10
	ds_read2_b32 v[70:71], v1 offset0:134 offset1:199
	v_add_u32_e32 v1, 0x800, v21
	ds_read2_b32 v[72:73], v1 offset0:8 offset1:73
	ds_read2_b32 v[74:75], v1 offset0:138 offset1:203
	v_add_u32_e32 v1, 0xc00, v21
	ds_read2_b32 v[76:77], v1 offset0:12 offset1:77
	ds_read2_b32 v[78:79], v1 offset0:142 offset1:207
	v_ashrrev_i32_e32 v1, 31, v0
	v_lshlrev_b64 v[0:1], 11, v[0:1]
	v_lshl_add_u64 v[0:1], s[2:3], 0, v[0:1]
	v_lshl_add_u64 v[0:1], v[10:11], 1, v[0:1]
	v_lshl_add_u64 v[0:1], v[0:1], 0, v[168:169]
	s_waitcnt lgkmcnt(0)
	v_cvt_pk_bf16_f32 v2, v64, v65
	v_cvt_pk_bf16_f32 v3, v66, v67
	v_cvt_pk_bf16_f32 v4, v68, v69
	v_cvt_pk_bf16_f32 v5, v70, v71
	v_cvt_pk_bf16_f32 v24, v72, v73
	v_cvt_pk_bf16_f32 v25, v74, v75
	v_cvt_pk_bf16_f32 v26, v76, v77
	v_cvt_pk_bf16_f32 v27, v78, v79
	global_store_dwordx4 v[0:1], v[2:5], off
	global_store_dwordx4 v[0:1], v[24:27], off offset:16
	s_branch .LBB0_1906

.LBB0_1949:
	s_or_b64 exec, exec, s[14:15]
	s_waitcnt lgkmcnt(0)
	s_barrier
	s_and_saveexec_b64 s[8:9], s[6:7]
	s_cbranch_execz .LBB0_1922
	v_add_u32_e32 v0, v10, v18
	v_cmp_gt_i32_e32 vcc, s94, v0
	s_and_b64 exec, exec, vcc
	s_cbranch_execz .LBB0_1922
	v_add_u32_e32 v1, 0x400, v26
	ds_read2_b32 v[64:65], v26 offset1:65
	ds_read2_b32 v[66:67], v26 offset0:130 offset1:195
	ds_read2_b32 v[68:69], v1 offset0:4 offset1:69
	v_ashrrev_i32_e32 v9, 31, v8
	ds_read2_b32 v[70:71], v1 offset0:134 offset1:199
	v_add_u32_e32 v1, 0x800, v26
	ds_read2_b32 v[72:73], v1 offset0:8 offset1:73
	ds_read2_b32 v[74:75], v1 offset0:138 offset1:203
	v_add_u32_e32 v1, 0xc00, v26
	ds_read2_b32 v[76:77], v1 offset0:12 offset1:77
	ds_read2_b32 v[78:79], v1 offset0:142 offset1:207
	v_ashrrev_i32_e32 v1, 31, v0
	v_lshlrev_b64 v[0:1], 11, v[0:1]
	v_lshl_add_u64 v[0:1], s[4:5], 0, v[0:1]
	v_lshl_add_u64 v[0:1], v[8:9], 1, v[0:1]
	v_lshl_add_u64 v[0:1], v[0:1], 0, v[168:169]
	s_waitcnt lgkmcnt(0)
	v_cvt_pk_bf16_f32 v10, v64, v65
	v_cvt_pk_bf16_f32 v11, v66, v67
	v_cvt_pk_bf16_f32 v12, v68, v69
	v_cvt_pk_bf16_f32 v13, v70, v71
	v_cvt_pk_bf16_f32 v28, v72, v73
	v_cvt_pk_bf16_f32 v29, v74, v75
	v_cvt_pk_bf16_f32 v30, v76, v77
	v_cvt_pk_bf16_f32 v31, v78, v79
	global_store_dwordx4 v[0:1], v[10:13], off
	global_store_dwordx4 v[0:1], v[28:31], off offset:16
	s_branch .LBB0_1922

.LBB0_1965:
	s_or_b64 exec, exec, s[4:5]
	s_waitcnt lgkmcnt(0)
	s_barrier
	s_and_saveexec_b64 s[4:5], vcc
	s_cbranch_execz .LBB0_1954
	v_add_u32_e32 v0, v12, v16
	v_cmp_gt_i32_e32 vcc, s92, v0
	s_and_b64 exec, exec, vcc
	s_cbranch_execz .LBB0_1954
	v_add_u32_e32 v1, 0x400, v21
	ds_read2_b32 v[64:65], v21 offset1:65
	ds_read2_b32 v[66:67], v21 offset0:130 offset1:195
	ds_read2_b32 v[68:69], v1 offset0:4 offset1:69
	v_ashrrev_i32_e32 v11, 31, v10
	ds_read2_b32 v[70:71], v1 offset0:134 offset1:199
	v_add_u32_e32 v1, 0x800, v21
	ds_read2_b32 v[72:73], v1 offset0:8 offset1:73
	ds_read2_b32 v[74:75], v1 offset0:138 offset1:203
	v_add_u32_e32 v1, 0xc00, v21
	ds_read2_b32 v[76:77], v1 offset0:12 offset1:77
	ds_read2_b32 v[78:79], v1 offset0:142 offset1:207
	v_ashrrev_i32_e32 v1, 31, v0
	v_lshlrev_b64 v[0:1], 13, v[0:1]
	v_lshl_add_u64 v[0:1], s[2:3], 0, v[0:1]
	v_lshl_add_u64 v[0:1], v[10:11], 1, v[0:1]
	v_lshl_add_u64 v[0:1], v[0:1], 0, v[168:169]
	s_waitcnt lgkmcnt(0)
	v_cvt_pk_bf16_f32 v2, v64, v65
	v_cvt_pk_bf16_f32 v3, v66, v67
	v_cvt_pk_bf16_f32 v4, v68, v69
	v_cvt_pk_bf16_f32 v5, v70, v71
	v_cvt_pk_bf16_f32 v24, v72, v73
	v_cvt_pk_bf16_f32 v25, v74, v75
	v_cvt_pk_bf16_f32 v26, v76, v77
	v_cvt_pk_bf16_f32 v27, v78, v79
	global_store_dwordx4 v[0:1], v[2:5], off
	global_store_dwordx4 v[0:1], v[24:27], off offset:16
	s_branch .LBB0_1954

.LBB0_1970:
	s_or_b64 exec, exec, s[4:5]
	s_waitcnt lgkmcnt(0)
	s_barrier
	s_and_saveexec_b64 s[4:5], s[6:7]
	s_cbranch_execz .LBB0_1972
	v_and_b32_e32 v1, 48, v1
	v_mul_u32_u24_e32 v3, 0x104, v1
	v_lshlrev_b32_e32 v4, 2, v2
	v_add3_u32 v14, s89, v3, v4
	v_add_u32_e32 v12, 0x400, v14
	ds_read2_b32 v[64:65], v14 offset1:65
	ds_read2_b32 v[66:67], v14 offset0:130 offset1:195
	ds_read2_b32 v[68:69], v12 offset0:4 offset1:69
	v_ashrrev_i32_e32 v3, 31, v2
	v_lshlrev_b64 v[2:3], 7, v[2:3]
	v_lshl_add_u64 v[2:3], s[82:83], 0, v[2:3]
	v_lshlrev_b32_e32 v168, 1, v1
	v_add_u32_e32 v1, 0x800, v14
	v_lshl_add_u64 v[10:11], v[2:3], 0, v[168:169]
	ds_read2_b32 v[70:71], v12 offset0:134 offset1:199
	ds_read2_b32 v[72:73], v1 offset0:8 offset1:73
	ds_read2_b32 v[74:75], v1 offset0:138 offset1:203
	v_add_u32_e32 v1, 0xc00, v14
	ds_read2_b32 v[76:77], v1 offset0:12 offset1:77
	ds_read2_b32 v[78:79], v1 offset0:142 offset1:207
	v_ashrrev_i32_e32 v1, 31, v0
	v_lshl_add_u64 v[0:1], v[0:1], 1, v[10:11]
	s_mov_b64 s[6:7], 0x1e30000
	v_lshl_add_u64 v[10:11], v[0:1], 0, s[6:7]
	v_add_co_u32_e32 v0, vcc, 0x1e30000, v0
	v_addc_co_u32_e32 v1, vcc, 0, v1, vcc
	s_waitcnt lgkmcnt(0)
	v_cvt_pk_bf16_f32 v2, v64, v65
	v_cvt_pk_bf16_f32 v3, v66, v67
	v_cvt_pk_bf16_f32 v4, v68, v69
	v_cvt_pk_bf16_f32 v5, v70, v71
	v_cvt_pk_bf16_f32 v6, v72, v73
	v_cvt_pk_bf16_f32 v7, v74, v75
	v_cvt_pk_bf16_f32 v8, v76, v77
	v_cvt_pk_bf16_f32 v9, v78, v79
	global_store_dwordx4 v[0:1], v[2:5], off
	global_store_dwordx4 v[10:11], v[6:9], off offset:16

.LBB0_1974:
	s_or_b64 exec, exec, s[6:7]
	s_waitcnt lgkmcnt(0)
	s_barrier
	s_and_saveexec_b64 s[6:7], s[8:9]
	s_cbranch_execz .LBB0_1976
	v_and_b32_e32 v1, 48, v1
	v_mul_u32_u24_e32 v3, 0x104, v1
	v_lshlrev_b32_e32 v4, 2, v2
	v_add3_u32 v14, s89, v3, v4
	v_add_u32_e32 v12, 0x400, v14
	ds_read2_b32 v[64:65], v14 offset1:65
	ds_read2_b32 v[66:67], v14 offset0:130 offset1:195
	ds_read2_b32 v[68:69], v12 offset0:4 offset1:69
	v_ashrrev_i32_e32 v3, 31, v2
	v_lshlrev_b64 v[2:3], 7, v[2:3]
	v_lshl_add_u64 v[2:3], s[82:83], 0, v[2:3]
	v_lshlrev_b32_e32 v168, 1, v1
	v_add_u32_e32 v1, 0x800, v14
	v_lshl_add_u64 v[10:11], v[2:3], 0, v[168:169]
	ds_read2_b32 v[70:71], v12 offset0:134 offset1:199
	ds_read2_b32 v[72:73], v1 offset0:8 offset1:73
	ds_read2_b32 v[74:75], v1 offset0:138 offset1:203
	v_add_u32_e32 v1, 0xc00, v14
	ds_read2_b32 v[76:77], v1 offset0:12 offset1:77
	ds_read2_b32 v[78:79], v1 offset0:142 offset1:207
	v_ashrrev_i32_e32 v1, 31, v0
	v_lshl_add_u64 v[0:1], v[0:1], 1, v[10:11]
	s_mov_b64 s[8:9], 0x1e38000
	v_lshl_add_u64 v[10:11], v[0:1], 0, s[8:9]
	v_add_co_u32_e32 v0, vcc, 0x1e38000, v0
	v_addc_co_u32_e32 v1, vcc, 0, v1, vcc
	s_waitcnt lgkmcnt(0)
	v_cvt_pk_bf16_f32 v2, v64, v65
	v_cvt_pk_bf16_f32 v3, v66, v67
	v_cvt_pk_bf16_f32 v4, v68, v69
	v_cvt_pk_bf16_f32 v5, v70, v71
	v_cvt_pk_bf16_f32 v6, v72, v73
	v_cvt_pk_bf16_f32 v7, v74, v75
	v_cvt_pk_bf16_f32 v8, v76, v77
	v_cvt_pk_bf16_f32 v9, v78, v79
	global_store_dwordx4 v[0:1], v[2:5], off
	global_store_dwordx4 v[10:11], v[6:9], off offset:16

.LBB0_1978:
	s_or_b64 exec, exec, s[6:7]
	s_waitcnt lgkmcnt(0)
	s_barrier
	s_and_saveexec_b64 s[6:7], s[8:9]
	s_cbranch_execz .LBB0_1980
	v_and_b32_e32 v1, 48, v1
	v_mul_u32_u24_e32 v3, 0x104, v1
	v_lshlrev_b32_e32 v4, 2, v2
	v_add3_u32 v14, s89, v3, v4
	v_add_u32_e32 v12, 0x400, v14
	ds_read2_b32 v[64:65], v14 offset1:65
	ds_read2_b32 v[66:67], v14 offset0:130 offset1:195
	ds_read2_b32 v[68:69], v12 offset0:4 offset1:69
	v_ashrrev_i32_e32 v3, 31, v2
	v_lshlrev_b64 v[2:3], 7, v[2:3]
	v_lshl_add_u64 v[2:3], s[82:83], 0, v[2:3]
	v_lshlrev_b32_e32 v168, 1, v1
	v_add_u32_e32 v1, 0x800, v14
	v_lshl_add_u64 v[10:11], v[2:3], 0, v[168:169]
	ds_read2_b32 v[70:71], v12 offset0:134 offset1:199
	ds_read2_b32 v[72:73], v1 offset0:8 offset1:73
	ds_read2_b32 v[74:75], v1 offset0:138 offset1:203
	v_add_u32_e32 v1, 0xc00, v14
	ds_read2_b32 v[76:77], v1 offset0:12 offset1:77
	ds_read2_b32 v[78:79], v1 offset0:142 offset1:207
	v_ashrrev_i32_e32 v1, 31, v0
	v_lshl_add_u64 v[0:1], v[0:1], 1, v[10:11]
	s_mov_b64 s[8:9], 0x1e32000
	v_lshl_add_u64 v[10:11], v[0:1], 0, s[8:9]
	v_add_co_u32_e32 v0, vcc, 0x1e32000, v0
	v_addc_co_u32_e32 v1, vcc, 0, v1, vcc
	s_waitcnt lgkmcnt(0)
	v_cvt_pk_bf16_f32 v2, v64, v65
	v_cvt_pk_bf16_f32 v3, v66, v67
	v_cvt_pk_bf16_f32 v4, v68, v69
	v_cvt_pk_bf16_f32 v5, v70, v71
	v_cvt_pk_bf16_f32 v6, v72, v73
	v_cvt_pk_bf16_f32 v7, v74, v75
	v_cvt_pk_bf16_f32 v8, v76, v77
	v_cvt_pk_bf16_f32 v9, v78, v79
	global_store_dwordx4 v[0:1], v[2:5], off
	global_store_dwordx4 v[10:11], v[6:9], off offset:16

.LBB0_1982:
	s_or_b64 exec, exec, s[6:7]
	s_waitcnt lgkmcnt(0)
	s_barrier
	s_and_saveexec_b64 s[6:7], s[8:9]
	s_cbranch_execz .LBB0_1984
	v_and_b32_e32 v1, 48, v1
	v_mul_u32_u24_e32 v3, 0x104, v1
	v_lshlrev_b32_e32 v4, 2, v2
	v_add3_u32 v14, s89, v3, v4
	v_add_u32_e32 v12, 0x400, v14
	ds_read2_b32 v[64:65], v14 offset1:65
	ds_read2_b32 v[66:67], v14 offset0:130 offset1:195
	ds_read2_b32 v[68:69], v12 offset0:4 offset1:69
	v_ashrrev_i32_e32 v3, 31, v2
	v_lshlrev_b64 v[2:3], 7, v[2:3]
	v_lshl_add_u64 v[2:3], s[82:83], 0, v[2:3]
	v_lshlrev_b32_e32 v168, 1, v1
	v_add_u32_e32 v1, 0x800, v14
	v_lshl_add_u64 v[10:11], v[2:3], 0, v[168:169]
	ds_read2_b32 v[70:71], v12 offset0:134 offset1:199
	ds_read2_b32 v[72:73], v1 offset0:8 offset1:73
	ds_read2_b32 v[74:75], v1 offset0:138 offset1:203
	v_add_u32_e32 v1, 0xc00, v14
	ds_read2_b32 v[76:77], v1 offset0:12 offset1:77
	ds_read2_b32 v[78:79], v1 offset0:142 offset1:207
	v_ashrrev_i32_e32 v1, 31, v0
	v_lshl_add_u64 v[0:1], v[0:1], 1, v[10:11]
	s_mov_b64 s[8:9], 0x1e3a000
	v_lshl_add_u64 v[10:11], v[0:1], 0, s[8:9]
	v_add_co_u32_e32 v0, vcc, 0x1e3a000, v0
	v_addc_co_u32_e32 v1, vcc, 0, v1, vcc
	s_waitcnt lgkmcnt(0)
	v_cvt_pk_bf16_f32 v2, v64, v65
	v_cvt_pk_bf16_f32 v3, v66, v67
	v_cvt_pk_bf16_f32 v4, v68, v69
	v_cvt_pk_bf16_f32 v5, v70, v71
	v_cvt_pk_bf16_f32 v6, v72, v73
	v_cvt_pk_bf16_f32 v7, v74, v75
	v_cvt_pk_bf16_f32 v8, v76, v77
	v_cvt_pk_bf16_f32 v9, v78, v79
	global_store_dwordx4 v[0:1], v[2:5], off
	global_store_dwordx4 v[10:11], v[6:9], off offset:16

.LBB0_1986:
	s_or_b64 exec, exec, s[6:7]
	s_waitcnt lgkmcnt(0)
	s_barrier
	s_and_saveexec_b64 s[6:7], s[8:9]
	s_cbranch_execz .LBB0_1988
	v_and_b32_e32 v1, 48, v1
	v_mul_u32_u24_e32 v3, 0x104, v1
	v_lshlrev_b32_e32 v4, 2, v2
	v_add3_u32 v14, s89, v3, v4
	v_add_u32_e32 v12, 0x400, v14
	ds_read2_b32 v[64:65], v14 offset1:65
	ds_read2_b32 v[66:67], v14 offset0:130 offset1:195
	ds_read2_b32 v[68:69], v12 offset0:4 offset1:69
	v_ashrrev_i32_e32 v3, 31, v2
	v_lshlrev_b64 v[2:3], 7, v[2:3]
	v_lshl_add_u64 v[2:3], s[82:83], 0, v[2:3]
	v_lshlrev_b32_e32 v168, 1, v1
	v_add_u32_e32 v1, 0x800, v14
	v_lshl_add_u64 v[10:11], v[2:3], 0, v[168:169]
	ds_read2_b32 v[70:71], v12 offset0:134 offset1:199
	ds_read2_b32 v[72:73], v1 offset0:8 offset1:73
	ds_read2_b32 v[74:75], v1 offset0:138 offset1:203
	v_add_u32_e32 v1, 0xc00, v14
	ds_read2_b32 v[76:77], v1 offset0:12 offset1:77
	ds_read2_b32 v[78:79], v1 offset0:142 offset1:207
	v_ashrrev_i32_e32 v1, 31, v0
	v_lshl_add_u64 v[0:1], v[0:1], 1, v[10:11]
	s_mov_b64 s[8:9], 0x1e34000
	v_lshl_add_u64 v[10:11], v[0:1], 0, s[8:9]
	v_add_co_u32_e32 v0, vcc, 0x1e34000, v0
	v_addc_co_u32_e32 v1, vcc, 0, v1, vcc
	s_waitcnt lgkmcnt(0)
	v_cvt_pk_bf16_f32 v2, v64, v65
	v_cvt_pk_bf16_f32 v3, v66, v67
	v_cvt_pk_bf16_f32 v4, v68, v69
	v_cvt_pk_bf16_f32 v5, v70, v71
	v_cvt_pk_bf16_f32 v6, v72, v73
	v_cvt_pk_bf16_f32 v7, v74, v75
	v_cvt_pk_bf16_f32 v8, v76, v77
	v_cvt_pk_bf16_f32 v9, v78, v79
	global_store_dwordx4 v[0:1], v[2:5], off
	global_store_dwordx4 v[10:11], v[6:9], off offset:16

.LBB0_1990:
	s_or_b64 exec, exec, s[6:7]
	s_waitcnt lgkmcnt(0)
	s_barrier
	s_and_saveexec_b64 s[6:7], s[8:9]
	s_cbranch_execz .LBB0_1992
	v_and_b32_e32 v1, 48, v1
	v_mul_u32_u24_e32 v3, 0x104, v1
	v_lshlrev_b32_e32 v4, 2, v2
	v_add3_u32 v14, s89, v3, v4
	v_add_u32_e32 v12, 0x400, v14
	ds_read2_b32 v[64:65], v14 offset1:65
	ds_read2_b32 v[66:67], v14 offset0:130 offset1:195
	ds_read2_b32 v[68:69], v12 offset0:4 offset1:69
	v_ashrrev_i32_e32 v3, 31, v2
	v_lshlrev_b64 v[2:3], 7, v[2:3]
	v_lshl_add_u64 v[2:3], s[82:83], 0, v[2:3]
	v_lshlrev_b32_e32 v168, 1, v1
	v_add_u32_e32 v1, 0x800, v14
	v_lshl_add_u64 v[10:11], v[2:3], 0, v[168:169]
	ds_read2_b32 v[70:71], v12 offset0:134 offset1:199
	ds_read2_b32 v[72:73], v1 offset0:8 offset1:73
	ds_read2_b32 v[74:75], v1 offset0:138 offset1:203
	v_add_u32_e32 v1, 0xc00, v14
	ds_read2_b32 v[76:77], v1 offset0:12 offset1:77
	ds_read2_b32 v[78:79], v1 offset0:142 offset1:207
	v_ashrrev_i32_e32 v1, 31, v0
	v_lshl_add_u64 v[0:1], v[0:1], 1, v[10:11]
	s_mov_b64 s[8:9], 0x1e3c000
	v_lshl_add_u64 v[10:11], v[0:1], 0, s[8:9]
	v_add_co_u32_e32 v0, vcc, 0x1e3c000, v0
	v_addc_co_u32_e32 v1, vcc, 0, v1, vcc
	s_waitcnt lgkmcnt(0)
	v_cvt_pk_bf16_f32 v2, v64, v65
	v_cvt_pk_bf16_f32 v3, v66, v67
	v_cvt_pk_bf16_f32 v4, v68, v69
	v_cvt_pk_bf16_f32 v5, v70, v71
	v_cvt_pk_bf16_f32 v6, v72, v73
	v_cvt_pk_bf16_f32 v7, v74, v75
	v_cvt_pk_bf16_f32 v8, v76, v77
	v_cvt_pk_bf16_f32 v9, v78, v79
	global_store_dwordx4 v[0:1], v[2:5], off
	global_store_dwordx4 v[10:11], v[6:9], off offset:16

.LBB0_1994:
	s_or_b64 exec, exec, s[6:7]
	s_waitcnt lgkmcnt(0)
	s_barrier
	s_and_saveexec_b64 s[2:3], s[8:9]
	s_cbranch_execz .LBB0_1996
	v_and_b32_e32 v1, 48, v1
	v_mul_u32_u24_e32 v3, 0x104, v1
	v_lshlrev_b32_e32 v4, 2, v2
	v_add3_u32 v14, s89, v3, v4
	v_add_u32_e32 v12, 0x400, v14
	ds_read2_b32 v[64:65], v14 offset1:65
	ds_read2_b32 v[66:67], v14 offset0:130 offset1:195
	ds_read2_b32 v[68:69], v12 offset0:4 offset1:69
	v_ashrrev_i32_e32 v3, 31, v2
	v_lshlrev_b64 v[2:3], 7, v[2:3]
	v_lshl_add_u64 v[2:3], s[82:83], 0, v[2:3]
	v_lshlrev_b32_e32 v168, 1, v1
	v_add_u32_e32 v1, 0x800, v14
	v_lshl_add_u64 v[10:11], v[2:3], 0, v[168:169]
	ds_read2_b32 v[70:71], v12 offset0:134 offset1:199
	ds_read2_b32 v[72:73], v1 offset0:8 offset1:73
	ds_read2_b32 v[74:75], v1 offset0:138 offset1:203
	v_add_u32_e32 v1, 0xc00, v14
	ds_read2_b32 v[76:77], v1 offset0:12 offset1:77
	ds_read2_b32 v[78:79], v1 offset0:142 offset1:207
	v_ashrrev_i32_e32 v1, 31, v0
	v_lshl_add_u64 v[0:1], v[0:1], 1, v[10:11]
	s_mov_b64 s[6:7], 0x1e36000
	v_lshl_add_u64 v[10:11], v[0:1], 0, s[6:7]
	v_add_co_u32_e32 v0, vcc, 0x1e36000, v0
	v_addc_co_u32_e32 v1, vcc, 0, v1, vcc
	s_waitcnt lgkmcnt(0)
	v_cvt_pk_bf16_f32 v2, v64, v65
	v_cvt_pk_bf16_f32 v3, v66, v67
	v_cvt_pk_bf16_f32 v4, v68, v69
	v_cvt_pk_bf16_f32 v5, v70, v71
	v_cvt_pk_bf16_f32 v6, v72, v73
	v_cvt_pk_bf16_f32 v7, v74, v75
	v_cvt_pk_bf16_f32 v8, v76, v77
	v_cvt_pk_bf16_f32 v9, v78, v79
	global_store_dwordx4 v[0:1], v[2:5], off
	global_store_dwordx4 v[10:11], v[6:9], off offset:16

.LBB0_1998:
	s_or_b64 exec, exec, s[2:3]
	s_waitcnt lgkmcnt(0)
	s_barrier
	s_and_saveexec_b64 s[2:3], s[6:7]
	s_cbranch_execz .LBB0_2000
	v_and_b32_e32 v1, 48, v1
	v_mul_u32_u24_e32 v3, 0x104, v1
	v_lshlrev_b32_e32 v4, 2, v2
	v_add3_u32 v14, s89, v3, v4
	v_add_u32_e32 v12, 0x400, v14
	ds_read2_b32 v[64:65], v14 offset1:65
	ds_read2_b32 v[66:67], v14 offset0:130 offset1:195
	ds_read2_b32 v[68:69], v12 offset0:4 offset1:69
	v_ashrrev_i32_e32 v3, 31, v2
	v_lshlrev_b64 v[2:3], 7, v[2:3]
	v_lshl_add_u64 v[2:3], s[82:83], 0, v[2:3]
	v_lshlrev_b32_e32 v168, 1, v1
	v_add_u32_e32 v1, 0x800, v14
	v_lshl_add_u64 v[10:11], v[2:3], 0, v[168:169]
	ds_read2_b32 v[70:71], v12 offset0:134 offset1:199
	ds_read2_b32 v[72:73], v1 offset0:8 offset1:73
	ds_read2_b32 v[74:75], v1 offset0:138 offset1:203
	v_add_u32_e32 v1, 0xc00, v14
	ds_read2_b32 v[76:77], v1 offset0:12 offset1:77
	ds_read2_b32 v[78:79], v1 offset0:142 offset1:207
	v_ashrrev_i32_e32 v1, 31, v0
	v_lshl_add_u64 v[0:1], v[0:1], 1, v[10:11]
	s_mov_b64 s[0:1], 0x1e3e000
	v_lshl_add_u64 v[10:11], v[0:1], 0, s[0:1]
	v_add_co_u32_e32 v0, vcc, 0x1e3e000, v0
	v_addc_co_u32_e32 v1, vcc, 0, v1, vcc
	s_waitcnt lgkmcnt(0)
	v_cvt_pk_bf16_f32 v2, v64, v65
	v_cvt_pk_bf16_f32 v3, v66, v67
	v_cvt_pk_bf16_f32 v4, v68, v69
	v_cvt_pk_bf16_f32 v5, v70, v71
	v_cvt_pk_bf16_f32 v6, v72, v73
	v_cvt_pk_bf16_f32 v7, v74, v75
	v_cvt_pk_bf16_f32 v8, v76, v77
	v_cvt_pk_bf16_f32 v9, v78, v79
	global_store_dwordx4 v[0:1], v[2:5], off
	global_store_dwordx4 v[10:11], v[6:9], off offset:16
